# v55 + one static s_setprio 1 for waves 4-7 before each of the five GEMM K-loops, every per-phase s_setprio flip inside the loops deleted (7.4)
# baseline (speedup 1.0000x reference)
.LBB0_123:
	s_ashr_i32 s51, s50, 31
	s_lshl_b64 s[22:23], s[50:51], 21
	s_add_u32 s52, s66, s22
	s_addc_u32 s53, s67, s23
	s_and_b64 s[22:23], s[12:13], exec
	s_cselect_b32 s15, s53, s17
	s_cselect_b32 s21, s52, s16
	s_ashr_i32 s49, s48, 31
	s_lshl_b64 s[22:23], s[48:49], 21
	s_add_u32 s54, s68, s22
	s_addc_u32 s55, s69, s23
	s_and_b64 s[22:23], s[12:13], exec
	s_cselect_b32 s24, s55, s19
	s_cselect_b32 s25, s54, s18
	s_add_u32 s16, s16, 0x100080
	s_addc_u32 s17, s17, 0
	s_add_u32 s49, s18, 0x100
	v_mov_b32_e32 v0, 0
	s_addc_u32 s51, s19, 0
	s_mov_b32 s56, -2
	v_mov_b32_e32 v1, v0
	v_mov_b32_e32 v2, v0
	v_mov_b32_e32 v3, v0
	v_mov_b32_e32 v4, v0
	v_mov_b32_e32 v5, v0
	v_mov_b32_e32 v6, v0
	v_mov_b32_e32 v7, v0
	v_mov_b32_e32 v16, v0
	v_mov_b32_e32 v17, v0
	v_mov_b32_e32 v18, v0
	v_mov_b32_e32 v19, v0
	v_mov_b32_e32 v20, v0
	v_mov_b32_e32 v21, v0
	v_mov_b32_e32 v22, v0
	v_mov_b32_e32 v23, v0
	v_mov_b32_e32 v32, v0
	v_mov_b32_e32 v33, v0
	v_mov_b32_e32 v34, v0
	v_mov_b32_e32 v35, v0
	v_mov_b32_e32 v36, v0
	v_mov_b32_e32 v37, v0
	v_mov_b32_e32 v38, v0
	v_mov_b32_e32 v39, v0
	v_mov_b32_e32 v48, v0
	v_mov_b32_e32 v49, v0
	v_mov_b32_e32 v50, v0
	v_mov_b32_e32 v51, v0
	v_mov_b32_e32 v52, v0
	v_mov_b32_e32 v53, v0
	v_mov_b32_e32 v54, v0
	v_mov_b32_e32 v55, v0
	v_mov_b32_e32 v8, v0
	v_mov_b32_e32 v9, v0
	v_mov_b32_e32 v10, v0
	v_mov_b32_e32 v11, v0
	v_mov_b32_e32 v12, v0
	v_mov_b32_e32 v13, v0
	v_mov_b32_e32 v14, v0
	v_mov_b32_e32 v15, v0
	v_mov_b32_e32 v24, v0
	v_mov_b32_e32 v25, v0
	v_mov_b32_e32 v26, v0
	v_mov_b32_e32 v27, v0
	v_mov_b32_e32 v28, v0
	v_mov_b32_e32 v29, v0
	v_mov_b32_e32 v30, v0
	v_mov_b32_e32 v31, v0
	v_mov_b32_e32 v40, v0
	v_mov_b32_e32 v41, v0
	v_mov_b32_e32 v42, v0
	v_mov_b32_e32 v43, v0
	v_mov_b32_e32 v44, v0
	v_mov_b32_e32 v45, v0
	v_mov_b32_e32 v46, v0
	v_mov_b32_e32 v47, v0
	v_mov_b32_e32 v56, v0
	v_mov_b32_e32 v57, v0
	v_mov_b32_e32 v58, v0
	v_mov_b32_e32 v59, v0
	v_mov_b32_e32 v60, v0
	v_mov_b32_e32 v61, v0
	v_mov_b32_e32 v62, v0
	v_mov_b32_e32 v63, v0
	v_mov_b32_e32 v64, v0
	v_mov_b32_e32 v65, v0
	v_mov_b32_e32 v66, v0
	v_mov_b32_e32 v67, v0
	v_mov_b32_e32 v68, v0
	v_mov_b32_e32 v69, v0
	v_mov_b32_e32 v70, v0
	v_mov_b32_e32 v71, v0
	v_mov_b32_e32 v80, v0
	v_mov_b32_e32 v81, v0
	v_mov_b32_e32 v82, v0
	v_mov_b32_e32 v83, v0
	v_mov_b32_e32 v84, v0
	v_mov_b32_e32 v85, v0
	v_mov_b32_e32 v86, v0
	v_mov_b32_e32 v87, v0
	v_mov_b32_e32 v96, v0
	v_mov_b32_e32 v97, v0
	v_mov_b32_e32 v98, v0
	v_mov_b32_e32 v99, v0
	v_mov_b32_e32 v100, v0
	v_mov_b32_e32 v101, v0
	v_mov_b32_e32 v102, v0
	v_mov_b32_e32 v103, v0
	v_mov_b32_e32 v112, v0
	v_mov_b32_e32 v113, v0
	v_mov_b32_e32 v114, v0
	v_mov_b32_e32 v115, v0
	v_mov_b32_e32 v116, v0
	v_mov_b32_e32 v117, v0
	v_mov_b32_e32 v118, v0
	v_mov_b32_e32 v119, v0
	v_mov_b32_e32 v72, v0
	v_mov_b32_e32 v73, v0
	v_mov_b32_e32 v74, v0
	v_mov_b32_e32 v75, v0
	v_mov_b32_e32 v76, v0
	v_mov_b32_e32 v77, v0
	v_mov_b32_e32 v78, v0
	v_mov_b32_e32 v79, v0
	v_mov_b32_e32 v88, v0
	v_mov_b32_e32 v89, v0
	v_mov_b32_e32 v90, v0
	v_mov_b32_e32 v91, v0
	v_mov_b32_e32 v92, v0
	v_mov_b32_e32 v93, v0
	v_mov_b32_e32 v94, v0
	v_mov_b32_e32 v95, v0
	v_mov_b32_e32 v104, v0
	v_mov_b32_e32 v105, v0
	v_mov_b32_e32 v106, v0
	v_mov_b32_e32 v107, v0
	v_mov_b32_e32 v108, v0
	v_mov_b32_e32 v109, v0
	v_mov_b32_e32 v110, v0
	v_mov_b32_e32 v111, v0
	v_mov_b32_e32 v120, v0
	v_mov_b32_e32 v121, v0
	v_mov_b32_e32 v122, v0
	v_mov_b32_e32 v123, v0
	v_mov_b32_e32 v124, v0
	v_mov_b32_e32 v125, v0
	v_mov_b32_e32 v126, v0
	v_mov_b32_e32 v127, v0
	v_readlane_b32 s98, v250, 9
	s_nop 1
	s_cmp_lt_u32 s98, 4
	s_cbranch_scc1 .Lprio_skip0
	s_setprio 1
.Lprio_skip0:
.LBB0_124:
	ds_read_b128 v[154:157], v168
	ds_read_b128 v[158:161], v168 offset:1024
	ds_read_b128 v[162:165], v168 offset:2048
	ds_read_b128 v[172:175], v168 offset:3072
	ds_read_b128 v[176:179], v169
	ds_read_b128 v[180:183], v169 offset:1024
	ds_read_b128 v[184:187], v169 offset:2048
	ds_read_b128 v[188:191], v169 offset:3072
	s_add_u32 s18, s16, 0xfff00080
	s_addc_u32 s19, s17, -1
	s_cmp_eq_u32 s56, 60
	s_cselect_b32 s23, s15, s19
	s_cselect_b32 s22, s21, s18
	s_cselect_b32 s19, s24, s51
	s_cselect_b32 s18, s25, s49
	s_add_i32 m0, s70, 0xc000
	ds_read_b128 v[192:195], v170
	ds_read_b128 v[196:199], v170 offset:1024
	ds_read_b128 v[200:203], v170 offset:2048
	ds_read_b128 v[204:207], v170 offset:3072
	ds_read_b128 v[208:211], v170 offset:4096
	ds_read_b128 v[212:215], v170 offset:5120
	ds_read_b128 v[216:219], v170 offset:6144
	ds_read_b128 v[220:223], v170 offset:7168
	global_load_lds_dwordx4 v146, s[16:17]
	s_add_i32 m0, s70, 0xe000
	s_nop 0
	global_load_lds_dwordx4 v148, s[16:17]
	s_waitcnt vmcnt(8)
	s_waitcnt lgkmcnt(0)
	s_barrier
	s_waitcnt lgkmcnt(0)
	v_mfma_f32_16x16x32_bf16 v[124:127], v[154:157], v[192:195], v[124:127]
	v_mfma_f32_16x16x32_bf16 v[120:123], v[162:165], v[192:195], v[120:123]
	v_mfma_f32_16x16x32_bf16 v[108:111], v[154:157], v[200:203], v[108:111]
	v_mfma_f32_16x16x32_bf16 v[104:107], v[162:165], v[200:203], v[104:107]
	v_mfma_f32_16x16x32_bf16 v[92:95], v[154:157], v[208:211], v[92:95]
	v_mfma_f32_16x16x32_bf16 v[88:91], v[162:165], v[208:211], v[88:91]
	v_mfma_f32_16x16x32_bf16 v[76:79], v[154:157], v[216:219], v[76:79]
	v_mfma_f32_16x16x32_bf16 v[72:75], v[162:165], v[216:219], v[72:75]
	v_mfma_f32_16x16x32_bf16 v[124:127], v[158:161], v[196:199], v[124:127]
	v_mfma_f32_16x16x32_bf16 v[120:123], v[172:175], v[196:199], v[120:123]
	v_mfma_f32_16x16x32_bf16 v[108:111], v[158:161], v[204:207], v[108:111]
	v_mfma_f32_16x16x32_bf16 v[104:107], v[172:175], v[204:207], v[104:107]
	v_mfma_f32_16x16x32_bf16 v[92:95], v[158:161], v[212:215], v[92:95]
	v_mfma_f32_16x16x32_bf16 v[88:91], v[172:175], v[212:215], v[88:91]
	v_mfma_f32_16x16x32_bf16 v[76:79], v[158:161], v[220:223], v[76:79]
	v_mfma_f32_16x16x32_bf16 v[72:75], v[172:175], v[220:223], v[72:75]
	v_mfma_f32_16x16x32_bf16 v[116:119], v[176:179], v[192:195], v[116:119]
	v_mfma_f32_16x16x32_bf16 v[112:115], v[184:187], v[192:195], v[112:115]
	v_mfma_f32_16x16x32_bf16 v[100:103], v[176:179], v[200:203], v[100:103]
	v_mfma_f32_16x16x32_bf16 v[96:99], v[184:187], v[200:203], v[96:99]
	v_mfma_f32_16x16x32_bf16 v[84:87], v[176:179], v[208:211], v[84:87]
	v_mfma_f32_16x16x32_bf16 v[80:83], v[184:187], v[208:211], v[80:83]
	v_mfma_f32_16x16x32_bf16 v[68:71], v[176:179], v[216:219], v[68:71]
	v_mfma_f32_16x16x32_bf16 v[64:67], v[184:187], v[216:219], v[64:67]
	v_mfma_f32_16x16x32_bf16 v[116:119], v[180:183], v[196:199], v[116:119]
	v_mfma_f32_16x16x32_bf16 v[112:115], v[188:191], v[196:199], v[112:115]
	v_mfma_f32_16x16x32_bf16 v[100:103], v[180:183], v[204:207], v[100:103]
	v_mfma_f32_16x16x32_bf16 v[96:99], v[188:191], v[204:207], v[96:99]
	v_mfma_f32_16x16x32_bf16 v[84:87], v[180:183], v[212:215], v[84:87]
	v_mfma_f32_16x16x32_bf16 v[80:83], v[188:191], v[212:215], v[80:83]
	v_mfma_f32_16x16x32_bf16 v[68:71], v[180:183], v[220:223], v[68:71]
	v_mfma_f32_16x16x32_bf16 v[64:67], v[188:191], v[220:223], v[64:67]
	s_barrier
	s_add_i32 s57, s77, s93
	s_mov_b32 m0, s57
	ds_read_b128 v[192:195], v170 offset:16384
	ds_read_b128 v[196:199], v170 offset:17408
	ds_read_b128 v[200:203], v170 offset:18432
	ds_read_b128 v[204:207], v170 offset:19456
	ds_read_b128 v[208:211], v170 offset:20480
	ds_read_b128 v[212:215], v170 offset:21504
	ds_read_b128 v[216:219], v170 offset:22528
	ds_read_b128 v[220:223], v170 offset:23552
	global_load_lds_dwordx4 v130, s[18:19]
	s_add_i32 m0, s57, 0x2000
	s_add_u32 s58, s18, 0x100000
	v_lshl_add_u64 v[224:225], s[18:19], 0, v[134:135]
	s_addc_u32 s59, s19, 0
	s_add_i32 s57, s78, s93
	global_load_lds_dwordx4 v134, s[18:19]
	s_mov_b32 m0, s57
	v_lshl_add_u64 v[228:229], s[22:23], 0, v[132:133]
	global_load_lds_dwordx4 v130, s[58:59]
	s_add_i32 m0, s57, 0x2000
	s_nop 0
	global_load_lds_dwordx4 v134, s[58:59]
	v_lshl_add_u64 v[226:227], s[22:23], 0, v[128:129]
	s_mov_b32 m0, s70
	s_nop 0
	global_load_lds_dwordx4 v128, s[22:23]
	s_mov_b32 m0, s71
	s_nop 0
	global_load_lds_dwordx4 v132, s[22:23]
	s_waitcnt vmcnt(8)
	s_waitcnt lgkmcnt(0)
	s_barrier
	s_waitcnt lgkmcnt(0)
	v_mfma_f32_16x16x32_bf16 v[60:63], v[154:157], v[192:195], v[60:63]
	v_mfma_f32_16x16x32_bf16 v[56:59], v[162:165], v[192:195], v[56:59]
	v_mfma_f32_16x16x32_bf16 v[44:47], v[154:157], v[200:203], v[44:47]
	v_mfma_f32_16x16x32_bf16 v[40:43], v[162:165], v[200:203], v[40:43]
	v_mfma_f32_16x16x32_bf16 v[28:31], v[154:157], v[208:211], v[28:31]
	v_mfma_f32_16x16x32_bf16 v[24:27], v[162:165], v[208:211], v[24:27]
	v_mfma_f32_16x16x32_bf16 v[12:15], v[154:157], v[216:219], v[12:15]
	v_mfma_f32_16x16x32_bf16 v[8:11], v[162:165], v[216:219], v[8:11]
	v_mfma_f32_16x16x32_bf16 v[60:63], v[158:161], v[196:199], v[60:63]
	v_mfma_f32_16x16x32_bf16 v[56:59], v[172:175], v[196:199], v[56:59]
	v_mfma_f32_16x16x32_bf16 v[44:47], v[158:161], v[204:207], v[44:47]
	v_mfma_f32_16x16x32_bf16 v[40:43], v[172:175], v[204:207], v[40:43]
	v_mfma_f32_16x16x32_bf16 v[28:31], v[158:161], v[212:215], v[28:31]
	v_mfma_f32_16x16x32_bf16 v[24:27], v[172:175], v[212:215], v[24:27]
	v_mfma_f32_16x16x32_bf16 v[12:15], v[158:161], v[220:223], v[12:15]
	v_mfma_f32_16x16x32_bf16 v[8:11], v[172:175], v[220:223], v[8:11]
	v_mfma_f32_16x16x32_bf16 v[52:55], v[176:179], v[192:195], v[52:55]
	v_mfma_f32_16x16x32_bf16 v[48:51], v[184:187], v[192:195], v[48:51]
	v_mfma_f32_16x16x32_bf16 v[36:39], v[176:179], v[200:203], v[36:39]
	v_mfma_f32_16x16x32_bf16 v[32:35], v[184:187], v[200:203], v[32:35]
	v_mfma_f32_16x16x32_bf16 v[20:23], v[176:179], v[208:211], v[20:23]
	v_mfma_f32_16x16x32_bf16 v[16:19], v[184:187], v[208:211], v[16:19]
	v_mfma_f32_16x16x32_bf16 v[4:7], v[176:179], v[216:219], v[4:7]
	v_mfma_f32_16x16x32_bf16 v[0:3], v[184:187], v[216:219], v[0:3]
	v_mfma_f32_16x16x32_bf16 v[52:55], v[180:183], v[196:199], v[52:55]
	v_mfma_f32_16x16x32_bf16 v[48:51], v[188:191], v[196:199], v[48:51]
	v_mfma_f32_16x16x32_bf16 v[36:39], v[180:183], v[204:207], v[36:39]
	v_mfma_f32_16x16x32_bf16 v[32:35], v[188:191], v[204:207], v[32:35]
	v_mfma_f32_16x16x32_bf16 v[20:23], v[180:183], v[212:215], v[20:23]
	v_mfma_f32_16x16x32_bf16 v[16:19], v[188:191], v[212:215], v[16:19]
	v_mfma_f32_16x16x32_bf16 v[4:7], v[180:183], v[220:223], v[4:7]
	v_mfma_f32_16x16x32_bf16 v[0:3], v[188:191], v[220:223], v[0:3]
	s_barrier
	s_add_i32 s57, 0, 0x18000
	v_add_u32_e32 v171, s57, v141
	s_add_i32 s58, 0, 0x1c000
	ds_read_b128 v[154:157], v171
	ds_read_b128 v[158:161], v171 offset:1024
	ds_read_b128 v[162:165], v171 offset:2048
	ds_read_b128 v[172:175], v171 offset:3072
	v_add_u32_e32 v171, s58, v141
	ds_read_b128 v[176:179], v171
	ds_read_b128 v[180:183], v171 offset:1024
	ds_read_b128 v[184:187], v171 offset:2048
	ds_read_b128 v[188:191], v171 offset:3072
	s_add_u32 s22, s22, 0x100000
	s_addc_u32 s23, s23, 0
	s_mov_b32 m0, s72
	ds_read_b128 v[192:195], v170 offset:32768
	ds_read_b128 v[196:199], v170 offset:33792
	ds_read_b128 v[200:203], v170 offset:34816
	ds_read_b128 v[204:207], v170 offset:35840
	ds_read_b128 v[208:211], v170 offset:36864
	ds_read_b128 v[212:215], v170 offset:37888
	ds_read_b128 v[216:219], v170 offset:38912
	ds_read_b128 v[220:223], v170 offset:39936
	global_load_lds_dwordx4 v128, s[22:23]
	s_mov_b32 m0, s73
	s_nop 0
	global_load_lds_dwordx4 v132, s[22:23]
	s_waitcnt vmcnt(8)
	s_waitcnt lgkmcnt(0)
	s_barrier
	s_waitcnt lgkmcnt(0)
	v_mfma_f32_16x16x32_bf16 v[124:127], v[154:157], v[192:195], v[124:127]
	v_mfma_f32_16x16x32_bf16 v[120:123], v[162:165], v[192:195], v[120:123]
	v_mfma_f32_16x16x32_bf16 v[108:111], v[154:157], v[200:203], v[108:111]
	v_mfma_f32_16x16x32_bf16 v[104:107], v[162:165], v[200:203], v[104:107]
	v_mfma_f32_16x16x32_bf16 v[92:95], v[154:157], v[208:211], v[92:95]
	v_mfma_f32_16x16x32_bf16 v[88:91], v[162:165], v[208:211], v[88:91]
	v_mfma_f32_16x16x32_bf16 v[76:79], v[154:157], v[216:219], v[76:79]
	v_mfma_f32_16x16x32_bf16 v[72:75], v[162:165], v[216:219], v[72:75]
	v_mfma_f32_16x16x32_bf16 v[124:127], v[158:161], v[196:199], v[124:127]
	v_mfma_f32_16x16x32_bf16 v[120:123], v[172:175], v[196:199], v[120:123]
	v_mfma_f32_16x16x32_bf16 v[108:111], v[158:161], v[204:207], v[108:111]
	v_mfma_f32_16x16x32_bf16 v[104:107], v[172:175], v[204:207], v[104:107]
	v_mfma_f32_16x16x32_bf16 v[92:95], v[158:161], v[212:215], v[92:95]
	v_mfma_f32_16x16x32_bf16 v[88:91], v[172:175], v[212:215], v[88:91]
	v_mfma_f32_16x16x32_bf16 v[76:79], v[158:161], v[220:223], v[76:79]
	v_mfma_f32_16x16x32_bf16 v[72:75], v[172:175], v[220:223], v[72:75]
	v_mfma_f32_16x16x32_bf16 v[116:119], v[176:179], v[192:195], v[116:119]
	v_mfma_f32_16x16x32_bf16 v[112:115], v[184:187], v[192:195], v[112:115]
	v_mfma_f32_16x16x32_bf16 v[100:103], v[176:179], v[200:203], v[100:103]
	v_mfma_f32_16x16x32_bf16 v[96:99], v[184:187], v[200:203], v[96:99]
	v_mfma_f32_16x16x32_bf16 v[84:87], v[176:179], v[208:211], v[84:87]
	v_mfma_f32_16x16x32_bf16 v[80:83], v[184:187], v[208:211], v[80:83]
	v_mfma_f32_16x16x32_bf16 v[68:71], v[176:179], v[216:219], v[68:71]
	v_mfma_f32_16x16x32_bf16 v[64:67], v[184:187], v[216:219], v[64:67]
	v_mfma_f32_16x16x32_bf16 v[116:119], v[180:183], v[196:199], v[116:119]
	v_mfma_f32_16x16x32_bf16 v[112:115], v[188:191], v[196:199], v[112:115]
	v_mfma_f32_16x16x32_bf16 v[100:103], v[180:183], v[204:207], v[100:103]
	v_mfma_f32_16x16x32_bf16 v[96:99], v[188:191], v[204:207], v[96:99]
	v_mfma_f32_16x16x32_bf16 v[84:87], v[180:183], v[212:215], v[84:87]
	v_mfma_f32_16x16x32_bf16 v[80:83], v[188:191], v[212:215], v[80:83]
	v_mfma_f32_16x16x32_bf16 v[68:71], v[180:183], v[220:223], v[68:71]
	v_mfma_f32_16x16x32_bf16 v[64:67], v[188:191], v[220:223], v[64:67]
	s_barrier
	s_add_i32 s22, s57, s93
	s_add_i32 m0, s22, 0xffffff80
	ds_read_b128 v[192:195], v170 offset:49152
	ds_read_b128 v[196:199], v170 offset:50176
	ds_read_b128 v[200:203], v170 offset:51200
	ds_read_b128 v[204:207], v170 offset:52224
	ds_read_b128 v[208:211], v170 offset:53248
	ds_read_b128 v[212:215], v170 offset:54272
	ds_read_b128 v[216:219], v170 offset:55296
	ds_read_b128 v[220:223], v170 offset:56320
	global_load_lds_dwordx4 v130, s[18:19] offset:128
	s_add_i32 m0, s22, 0x2000
	s_add_u32 s18, s18, 0x100080
	v_lshl_add_u64 v[166:167], v[224:225], 0, s[26:27]
	s_addc_u32 s19, s19, 0
	s_add_i32 s22, s58, s93
	global_load_lds_dwordx4 v[166:167], off
	s_mov_b32 m0, s22
	s_nop 0
	global_load_lds_dwordx4 v130, s[18:19]
	s_add_i32 m0, s22, 0x2000
	s_nop 0
	global_load_lds_dwordx4 v134, s[18:19]
	v_lshl_add_u64 v[166:167], v[226:227], 0, s[26:27]
	s_mov_b32 m0, s75
	s_nop 0
	global_load_lds_dwordx4 v[166:167], off
	v_lshl_add_u64 v[166:167], v[228:229], 0, s[26:27]
	s_mov_b32 m0, s76
	s_nop 0
	global_load_lds_dwordx4 v[166:167], off
	s_waitcnt vmcnt(8)
	s_waitcnt lgkmcnt(0)
	s_barrier
	s_waitcnt lgkmcnt(0)
	v_mfma_f32_16x16x32_bf16 v[60:63], v[154:157], v[192:195], v[60:63]
	v_mfma_f32_16x16x32_bf16 v[56:59], v[162:165], v[192:195], v[56:59]
	v_mfma_f32_16x16x32_bf16 v[44:47], v[154:157], v[200:203], v[44:47]
	v_mfma_f32_16x16x32_bf16 v[40:43], v[162:165], v[200:203], v[40:43]
	v_mfma_f32_16x16x32_bf16 v[28:31], v[154:157], v[208:211], v[28:31]
	v_mfma_f32_16x16x32_bf16 v[24:27], v[162:165], v[208:211], v[24:27]
	v_mfma_f32_16x16x32_bf16 v[12:15], v[154:157], v[216:219], v[12:15]
	v_mfma_f32_16x16x32_bf16 v[8:11], v[162:165], v[216:219], v[8:11]
	v_mfma_f32_16x16x32_bf16 v[60:63], v[158:161], v[196:199], v[60:63]
	v_mfma_f32_16x16x32_bf16 v[56:59], v[172:175], v[196:199], v[56:59]
	v_mfma_f32_16x16x32_bf16 v[44:47], v[158:161], v[204:207], v[44:47]
	v_mfma_f32_16x16x32_bf16 v[40:43], v[172:175], v[204:207], v[40:43]
	v_mfma_f32_16x16x32_bf16 v[28:31], v[158:161], v[212:215], v[28:31]
	v_mfma_f32_16x16x32_bf16 v[24:27], v[172:175], v[212:215], v[24:27]
	v_mfma_f32_16x16x32_bf16 v[12:15], v[158:161], v[220:223], v[12:15]
	v_mfma_f32_16x16x32_bf16 v[8:11], v[172:175], v[220:223], v[8:11]
	v_mfma_f32_16x16x32_bf16 v[52:55], v[176:179], v[192:195], v[52:55]
	v_mfma_f32_16x16x32_bf16 v[48:51], v[184:187], v[192:195], v[48:51]
	v_mfma_f32_16x16x32_bf16 v[36:39], v[176:179], v[200:203], v[36:39]
	v_mfma_f32_16x16x32_bf16 v[32:35], v[184:187], v[200:203], v[32:35]
	v_mfma_f32_16x16x32_bf16 v[20:23], v[176:179], v[208:211], v[20:23]
	v_mfma_f32_16x16x32_bf16 v[16:19], v[184:187], v[208:211], v[16:19]
	v_mfma_f32_16x16x32_bf16 v[4:7], v[176:179], v[216:219], v[4:7]
	v_mfma_f32_16x16x32_bf16 v[0:3], v[184:187], v[216:219], v[0:3]
	v_mfma_f32_16x16x32_bf16 v[52:55], v[180:183], v[196:199], v[52:55]
	v_mfma_f32_16x16x32_bf16 v[48:51], v[188:191], v[196:199], v[48:51]
	v_mfma_f32_16x16x32_bf16 v[36:39], v[180:183], v[204:207], v[36:39]
	v_mfma_f32_16x16x32_bf16 v[32:35], v[188:191], v[204:207], v[32:35]
	v_mfma_f32_16x16x32_bf16 v[20:23], v[180:183], v[212:215], v[20:23]
	v_mfma_f32_16x16x32_bf16 v[16:19], v[188:191], v[212:215], v[16:19]
	v_mfma_f32_16x16x32_bf16 v[4:7], v[180:183], v[220:223], v[4:7]
	v_mfma_f32_16x16x32_bf16 v[0:3], v[188:191], v[220:223], v[0:3]
	s_barrier
	s_add_i32 s56, s56, 2
	s_add_u32 s16, s16, 0x100
	s_addc_u32 s17, s17, 0
	s_add_u32 s49, s49, 0x100
	s_addc_u32 s51, s51, 0
	s_cmp_lt_u32 s56, 62
	s_cbranch_scc1 .LBB0_124
	s_setprio 0
	s_andn2_b64 vcc, exec, s[94:95]
	s_cbranch_vccnz .LBB0_127
	s_barrier

.LBB0_1153:
	s_mov_b32 s34, s31
	s_mov_b32 s30, s35
	s_ashr_i32 s35, s31, 31
	s_lshl_b64 s[38:39], s[34:35], 21
	s_add_u32 s31, s25, s38
	s_mov_b32 s28, s40
	s_mov_b32 s74, s29
	s_addc_u32 s35, s50, s39
	s_ashr_i32 s29, s40, 31
	s_mov_b32 s73, s41
	s_lshl_b64 s[40:41], s[28:29], 7
	s_add_u32 s38, s31, s40
	s_addc_u32 s39, s35, s41
	s_and_b64 s[48:49], s[36:37], exec
	s_cselect_b32 s29, s39, s45
	s_cselect_b32 s35, s38, s44
	s_ashr_i32 s31, s30, 31
	s_lshl_b64 s[48:49], s[30:31], 21
	s_add_u32 s31, s51, s48
	s_addc_u32 s43, s52, s49
	s_add_u32 s40, s31, s40
	s_addc_u32 s41, s43, s41
	s_and_b64 s[48:49], s[36:37], exec
	s_cselect_b32 s31, s41, s47
	s_cselect_b32 s43, s40, s46
	s_add_i32 s75, s27, -2
	s_add_u32 s44, s44, 0x100080
	s_addc_u32 s45, s45, 0
	s_add_u32 s76, s46, 0x100
	v_mov_b32_e32 v0, 0
	s_addc_u32 s77, s47, 0
	s_mov_b32 s46, 0
	v_mov_b32_e32 v1, v0
	v_mov_b32_e32 v2, v0
	v_mov_b32_e32 v3, v0
	v_mov_b32_e32 v4, v0
	v_mov_b32_e32 v5, v0
	v_mov_b32_e32 v6, v0
	v_mov_b32_e32 v7, v0
	v_mov_b32_e32 v12, v0
	v_mov_b32_e32 v13, v0
	v_mov_b32_e32 v14, v0
	v_mov_b32_e32 v15, v0
	v_mov_b32_e32 v16, v0
	v_mov_b32_e32 v17, v0
	v_mov_b32_e32 v18, v0
	v_mov_b32_e32 v19, v0
	v_mov_b32_e32 v28, v0
	v_mov_b32_e32 v29, v0
	v_mov_b32_e32 v30, v0
	v_mov_b32_e32 v31, v0
	v_mov_b32_e32 v32, v0
	v_mov_b32_e32 v33, v0
	v_mov_b32_e32 v34, v0
	v_mov_b32_e32 v35, v0
	v_mov_b32_e32 v44, v0
	v_mov_b32_e32 v45, v0
	v_mov_b32_e32 v46, v0
	v_mov_b32_e32 v47, v0
	v_mov_b32_e32 v48, v0
	v_mov_b32_e32 v49, v0
	v_mov_b32_e32 v50, v0
	v_mov_b32_e32 v51, v0
	v_mov_b32_e32 v8, v0
	v_mov_b32_e32 v9, v0
	v_mov_b32_e32 v10, v0
	v_mov_b32_e32 v11, v0
	v_mov_b32_e32 v20, v0
	v_mov_b32_e32 v21, v0
	v_mov_b32_e32 v22, v0
	v_mov_b32_e32 v23, v0
	v_mov_b32_e32 v24, v0
	v_mov_b32_e32 v25, v0
	v_mov_b32_e32 v26, v0
	v_mov_b32_e32 v27, v0
	v_mov_b32_e32 v36, v0
	v_mov_b32_e32 v37, v0
	v_mov_b32_e32 v38, v0
	v_mov_b32_e32 v39, v0
	v_mov_b32_e32 v40, v0
	v_mov_b32_e32 v41, v0
	v_mov_b32_e32 v42, v0
	v_mov_b32_e32 v43, v0
	v_mov_b32_e32 v52, v0
	v_mov_b32_e32 v53, v0
	v_mov_b32_e32 v54, v0
	v_mov_b32_e32 v55, v0
	v_mov_b32_e32 v56, v0
	v_mov_b32_e32 v57, v0
	v_mov_b32_e32 v58, v0
	v_mov_b32_e32 v59, v0
	v_mov_b32_e32 v60, v0
	v_mov_b32_e32 v61, v0
	v_mov_b32_e32 v62, v0
	v_mov_b32_e32 v63, v0
	v_mov_b32_e32 v64, v0
	v_mov_b32_e32 v65, v0
	v_mov_b32_e32 v66, v0
	v_mov_b32_e32 v67, v0
	v_mov_b32_e32 v68, v0
	v_mov_b32_e32 v69, v0
	v_mov_b32_e32 v70, v0
	v_mov_b32_e32 v71, v0
	v_mov_b32_e32 v72, v0
	v_mov_b32_e32 v73, v0
	v_mov_b32_e32 v74, v0
	v_mov_b32_e32 v75, v0
	v_mov_b32_e32 v80, v0
	v_mov_b32_e32 v81, v0
	v_mov_b32_e32 v82, v0
	v_mov_b32_e32 v83, v0
	v_mov_b32_e32 v88, v0
	v_mov_b32_e32 v89, v0
	v_mov_b32_e32 v90, v0
	v_mov_b32_e32 v91, v0
	v_mov_b32_e32 v96, v0
	v_mov_b32_e32 v97, v0
	v_mov_b32_e32 v98, v0
	v_mov_b32_e32 v99, v0
	v_mov_b32_e32 v104, v0
	v_mov_b32_e32 v105, v0
	v_mov_b32_e32 v106, v0
	v_mov_b32_e32 v107, v0
	v_mov_b32_e32 v112, v0
	v_mov_b32_e32 v113, v0
	v_mov_b32_e32 v114, v0
	v_mov_b32_e32 v115, v0
	v_mov_b32_e32 v76, v0
	v_mov_b32_e32 v77, v0
	v_mov_b32_e32 v78, v0
	v_mov_b32_e32 v79, v0
	v_mov_b32_e32 v84, v0
	v_mov_b32_e32 v85, v0
	v_mov_b32_e32 v86, v0
	v_mov_b32_e32 v87, v0
	v_mov_b32_e32 v92, v0
	v_mov_b32_e32 v93, v0
	v_mov_b32_e32 v94, v0
	v_mov_b32_e32 v95, v0
	v_mov_b32_e32 v100, v0
	v_mov_b32_e32 v101, v0
	v_mov_b32_e32 v102, v0
	v_mov_b32_e32 v103, v0
	v_mov_b32_e32 v108, v0
	v_mov_b32_e32 v109, v0
	v_mov_b32_e32 v110, v0
	v_mov_b32_e32 v111, v0
	v_mov_b32_e32 v116, v0
	v_mov_b32_e32 v117, v0
	v_mov_b32_e32 v118, v0
	v_mov_b32_e32 v119, v0
	v_mov_b32_e32 v120, v0
	v_mov_b32_e32 v121, v0
	v_mov_b32_e32 v122, v0
	v_mov_b32_e32 v123, v0
	v_mov_b32_e32 v124, v0
	v_mov_b32_e32 v125, v0
	v_mov_b32_e32 v126, v0
	v_mov_b32_e32 v127, v0
	v_readlane_b32 s98, v250, 9
	s_nop 1
	s_cmp_lt_u32 s98, 4
	s_cbranch_scc1 .Lprio_skip1
	s_setprio 1
.Lprio_skip1:
.LBB0_1154:
	ds_read_b128 v[140:143], v157
	ds_read_b128 v[144:147], v157 offset:1024
	s_waitcnt lgkmcnt(0)
	ds_read_b128 v[148:151], v157 offset:2048
	ds_read_b128 v[162:165], v157 offset:3072
	ds_read_b128 v[166:169], v158
	ds_read_b128 v[170:173], v158 offset:1024
	ds_read_b128 v[174:177], v158 offset:2048
	ds_read_b128 v[178:181], v158 offset:3072
	s_add_i32 s72, s46, 2
	s_add_u32 s47, s44, 0xfff00080
	s_addc_u32 s48, s45, -1
	s_cmp_eq_u32 s75, s46
	s_cselect_b32 s46, s43, s76
	s_cselect_b32 s49, s29, s48
	s_cselect_b32 s48, s35, s47
	s_cselect_b32 s47, s31, s77
	s_add_i32 m0, s53, 0xc000
	ds_read_b128 v[182:185], v159
	ds_read_b128 v[186:189], v159 offset:1024
	ds_read_b128 v[190:193], v159 offset:2048
	ds_read_b128 v[194:197], v159 offset:3072
	ds_read_b128 v[198:201], v159 offset:4096
	ds_read_b128 v[202:205], v159 offset:5120
	ds_read_b128 v[206:209], v159 offset:6144
	ds_read_b128 v[210:213], v159 offset:7168
	global_load_lds_dwordx4 v134, s[44:45]
	s_add_i32 m0, s53, 0xe000
	s_nop 0
	global_load_lds_dwordx4 v136, s[44:45]
	s_waitcnt vmcnt(8)
	s_waitcnt lgkmcnt(0)
	s_barrier
	s_waitcnt lgkmcnt(0)
	v_mfma_f32_16x16x32_bf16 v[124:127], v[140:143], v[182:185], v[124:127]
	v_mfma_f32_16x16x32_bf16 v[120:123], v[148:151], v[182:185], v[120:123]
	v_mfma_f32_16x16x32_bf16 v[116:119], v[140:143], v[190:193], v[116:119]
	v_mfma_f32_16x16x32_bf16 v[108:111], v[148:151], v[190:193], v[108:111]
	v_mfma_f32_16x16x32_bf16 v[100:103], v[140:143], v[198:201], v[100:103]
	v_mfma_f32_16x16x32_bf16 v[92:95], v[148:151], v[198:201], v[92:95]
	v_mfma_f32_16x16x32_bf16 v[84:87], v[140:143], v[206:209], v[84:87]
	v_mfma_f32_16x16x32_bf16 v[76:79], v[148:151], v[206:209], v[76:79]
	v_mfma_f32_16x16x32_bf16 v[124:127], v[144:147], v[186:189], v[124:127]
	v_mfma_f32_16x16x32_bf16 v[120:123], v[162:165], v[186:189], v[120:123]
	v_mfma_f32_16x16x32_bf16 v[116:119], v[144:147], v[194:197], v[116:119]
	v_mfma_f32_16x16x32_bf16 v[108:111], v[162:165], v[194:197], v[108:111]
	v_mfma_f32_16x16x32_bf16 v[100:103], v[144:147], v[202:205], v[100:103]
	v_mfma_f32_16x16x32_bf16 v[92:95], v[162:165], v[202:205], v[92:95]
	v_mfma_f32_16x16x32_bf16 v[84:87], v[144:147], v[210:213], v[84:87]
	v_mfma_f32_16x16x32_bf16 v[76:79], v[162:165], v[210:213], v[76:79]
	v_mfma_f32_16x16x32_bf16 v[112:115], v[166:169], v[182:185], v[112:115]
	v_mfma_f32_16x16x32_bf16 v[104:107], v[174:177], v[182:185], v[104:107]
	v_mfma_f32_16x16x32_bf16 v[96:99], v[166:169], v[190:193], v[96:99]
	v_mfma_f32_16x16x32_bf16 v[88:91], v[174:177], v[190:193], v[88:91]
	v_mfma_f32_16x16x32_bf16 v[80:83], v[166:169], v[198:201], v[80:83]
	v_mfma_f32_16x16x32_bf16 v[72:75], v[174:177], v[198:201], v[72:75]
	v_mfma_f32_16x16x32_bf16 v[68:71], v[166:169], v[206:209], v[68:71]
	v_mfma_f32_16x16x32_bf16 v[64:67], v[174:177], v[206:209], v[64:67]
	v_mfma_f32_16x16x32_bf16 v[112:115], v[170:173], v[186:189], v[112:115]
	v_mfma_f32_16x16x32_bf16 v[104:107], v[178:181], v[186:189], v[104:107]
	v_mfma_f32_16x16x32_bf16 v[96:99], v[170:173], v[194:197], v[96:99]
	v_mfma_f32_16x16x32_bf16 v[88:91], v[178:181], v[194:197], v[88:91]
	v_mfma_f32_16x16x32_bf16 v[80:83], v[170:173], v[202:205], v[80:83]
	v_mfma_f32_16x16x32_bf16 v[72:75], v[178:181], v[202:205], v[72:75]
	v_mfma_f32_16x16x32_bf16 v[68:71], v[170:173], v[210:213], v[68:71]
	v_mfma_f32_16x16x32_bf16 v[64:67], v[178:181], v[210:213], v[64:67]
	s_barrier
	s_add_i32 s78, s62, s93
	s_mov_b32 m0, s78
	ds_read_b128 v[182:185], v159 offset:16384
	ds_read_b128 v[186:189], v159 offset:17408
	ds_read_b128 v[190:193], v159 offset:18432
	ds_read_b128 v[194:197], v159 offset:19456
	ds_read_b128 v[198:201], v159 offset:20480
	ds_read_b128 v[202:205], v159 offset:21504
	ds_read_b128 v[206:209], v159 offset:22528
	ds_read_b128 v[210:213], v159 offset:23552
	global_load_lds_dwordx4 v128, s[46:47]
	s_add_i32 m0, s78, 0x2000
	s_add_u32 s78, s46, 0x100000
	v_lshl_add_u64 v[216:217], s[46:47], 0, v[130:131]
	s_addc_u32 s79, s47, 0
	s_add_i32 s80, s63, s93
	global_load_lds_dwordx4 v130, s[46:47]
	s_mov_b32 m0, s80
	v_lshl_add_u64 v[220:221], s[48:49], 0, v[130:131]
	global_load_lds_dwordx4 v128, s[78:79]
	s_add_i32 m0, s80, 0x2000
	s_nop 0
	global_load_lds_dwordx4 v130, s[78:79]
	v_lshl_add_u64 v[218:219], s[48:49], 0, v[128:129]
	s_mov_b32 m0, s53
	s_nop 0
	global_load_lds_dwordx4 v128, s[48:49]
	s_mov_b32 m0, s54
	s_nop 0
	global_load_lds_dwordx4 v130, s[48:49]
	s_waitcnt vmcnt(8)
	s_waitcnt lgkmcnt(0)
	s_barrier
	s_waitcnt lgkmcnt(0)
	v_mfma_f32_16x16x32_bf16 v[60:63], v[140:143], v[182:185], v[60:63]
	v_mfma_f32_16x16x32_bf16 v[56:59], v[148:151], v[182:185], v[56:59]
	v_mfma_f32_16x16x32_bf16 v[52:55], v[140:143], v[190:193], v[52:55]
	v_mfma_f32_16x16x32_bf16 v[40:43], v[148:151], v[190:193], v[40:43]
	v_mfma_f32_16x16x32_bf16 v[36:39], v[140:143], v[198:201], v[36:39]
	v_mfma_f32_16x16x32_bf16 v[24:27], v[148:151], v[198:201], v[24:27]
	v_mfma_f32_16x16x32_bf16 v[20:23], v[140:143], v[206:209], v[20:23]
	v_mfma_f32_16x16x32_bf16 v[8:11], v[148:151], v[206:209], v[8:11]
	v_mfma_f32_16x16x32_bf16 v[60:63], v[144:147], v[186:189], v[60:63]
	v_mfma_f32_16x16x32_bf16 v[56:59], v[162:165], v[186:189], v[56:59]
	v_mfma_f32_16x16x32_bf16 v[52:55], v[144:147], v[194:197], v[52:55]
	v_mfma_f32_16x16x32_bf16 v[40:43], v[162:165], v[194:197], v[40:43]
	v_mfma_f32_16x16x32_bf16 v[36:39], v[144:147], v[202:205], v[36:39]
	v_mfma_f32_16x16x32_bf16 v[24:27], v[162:165], v[202:205], v[24:27]
	v_mfma_f32_16x16x32_bf16 v[20:23], v[144:147], v[210:213], v[20:23]
	v_mfma_f32_16x16x32_bf16 v[8:11], v[162:165], v[210:213], v[8:11]
	v_mfma_f32_16x16x32_bf16 v[48:51], v[166:169], v[182:185], v[48:51]
	v_mfma_f32_16x16x32_bf16 v[44:47], v[174:177], v[182:185], v[44:47]
	v_mfma_f32_16x16x32_bf16 v[32:35], v[166:169], v[190:193], v[32:35]
	v_mfma_f32_16x16x32_bf16 v[28:31], v[174:177], v[190:193], v[28:31]
	v_mfma_f32_16x16x32_bf16 v[16:19], v[166:169], v[198:201], v[16:19]
	v_mfma_f32_16x16x32_bf16 v[12:15], v[174:177], v[198:201], v[12:15]
	v_mfma_f32_16x16x32_bf16 v[4:7], v[166:169], v[206:209], v[4:7]
	v_mfma_f32_16x16x32_bf16 v[0:3], v[174:177], v[206:209], v[0:3]
	v_mfma_f32_16x16x32_bf16 v[48:51], v[170:173], v[186:189], v[48:51]
	v_mfma_f32_16x16x32_bf16 v[44:47], v[178:181], v[186:189], v[44:47]
	v_mfma_f32_16x16x32_bf16 v[32:35], v[170:173], v[194:197], v[32:35]
	v_mfma_f32_16x16x32_bf16 v[28:31], v[178:181], v[194:197], v[28:31]
	v_mfma_f32_16x16x32_bf16 v[16:19], v[170:173], v[202:205], v[16:19]
	v_mfma_f32_16x16x32_bf16 v[12:15], v[178:181], v[202:205], v[12:15]
	v_mfma_f32_16x16x32_bf16 v[4:7], v[170:173], v[210:213], v[4:7]
	v_mfma_f32_16x16x32_bf16 v[0:3], v[178:181], v[210:213], v[0:3]
	s_barrier
	s_add_i32 s78, 0, 0x18000
	v_add_u32_e32 v133, s78, v153
	s_add_i32 s79, 0, 0x1c000
	ds_read_b128 v[140:143], v133
	ds_read_b128 v[144:147], v133 offset:1024
	ds_read_b128 v[148:151], v133 offset:2048
	ds_read_b128 v[162:165], v133 offset:3072
	v_add_u32_e32 v133, s79, v153
	ds_read_b128 v[166:169], v133
	ds_read_b128 v[170:173], v133 offset:1024
	ds_read_b128 v[174:177], v133 offset:2048
	ds_read_b128 v[178:181], v133 offset:3072
	s_add_u32 s48, s48, 0x100000
	s_addc_u32 s49, s49, 0
	s_mov_b32 m0, s55
	ds_read_b128 v[182:185], v159 offset:32768
	ds_read_b128 v[186:189], v159 offset:33792
	ds_read_b128 v[190:193], v159 offset:34816
	ds_read_b128 v[194:197], v159 offset:35840
	ds_read_b128 v[198:201], v159 offset:36864
	ds_read_b128 v[202:205], v159 offset:37888
	ds_read_b128 v[206:209], v159 offset:38912
	ds_read_b128 v[210:213], v159 offset:39936
	global_load_lds_dwordx4 v128, s[48:49]
	s_mov_b32 m0, s56
	s_nop 0
	global_load_lds_dwordx4 v130, s[48:49]
	s_waitcnt vmcnt(8)
	s_waitcnt lgkmcnt(0)
	s_barrier
	s_waitcnt lgkmcnt(0)
	v_mfma_f32_16x16x32_bf16 v[124:127], v[140:143], v[182:185], v[124:127]
	v_mfma_f32_16x16x32_bf16 v[120:123], v[148:151], v[182:185], v[120:123]
	v_mfma_f32_16x16x32_bf16 v[116:119], v[140:143], v[190:193], v[116:119]
	v_mfma_f32_16x16x32_bf16 v[108:111], v[148:151], v[190:193], v[108:111]
	v_mfma_f32_16x16x32_bf16 v[100:103], v[140:143], v[198:201], v[100:103]
	v_mfma_f32_16x16x32_bf16 v[92:95], v[148:151], v[198:201], v[92:95]
	v_mfma_f32_16x16x32_bf16 v[84:87], v[140:143], v[206:209], v[84:87]
	v_mfma_f32_16x16x32_bf16 v[76:79], v[148:151], v[206:209], v[76:79]
	v_mfma_f32_16x16x32_bf16 v[124:127], v[144:147], v[186:189], v[124:127]
	v_mfma_f32_16x16x32_bf16 v[120:123], v[162:165], v[186:189], v[120:123]
	v_mfma_f32_16x16x32_bf16 v[116:119], v[144:147], v[194:197], v[116:119]
	v_mfma_f32_16x16x32_bf16 v[108:111], v[162:165], v[194:197], v[108:111]
	v_mfma_f32_16x16x32_bf16 v[100:103], v[144:147], v[202:205], v[100:103]
	v_mfma_f32_16x16x32_bf16 v[92:95], v[162:165], v[202:205], v[92:95]
	v_mfma_f32_16x16x32_bf16 v[84:87], v[144:147], v[210:213], v[84:87]
	v_mfma_f32_16x16x32_bf16 v[76:79], v[162:165], v[210:213], v[76:79]
	v_mfma_f32_16x16x32_bf16 v[112:115], v[166:169], v[182:185], v[112:115]
	v_mfma_f32_16x16x32_bf16 v[104:107], v[174:177], v[182:185], v[104:107]
	v_mfma_f32_16x16x32_bf16 v[96:99], v[166:169], v[190:193], v[96:99]
	v_mfma_f32_16x16x32_bf16 v[88:91], v[174:177], v[190:193], v[88:91]
	v_mfma_f32_16x16x32_bf16 v[80:83], v[166:169], v[198:201], v[80:83]
	v_mfma_f32_16x16x32_bf16 v[72:75], v[174:177], v[198:201], v[72:75]
	v_mfma_f32_16x16x32_bf16 v[68:71], v[166:169], v[206:209], v[68:71]
	v_mfma_f32_16x16x32_bf16 v[64:67], v[174:177], v[206:209], v[64:67]
	v_mfma_f32_16x16x32_bf16 v[112:115], v[170:173], v[186:189], v[112:115]
	v_mfma_f32_16x16x32_bf16 v[104:107], v[178:181], v[186:189], v[104:107]
	v_mfma_f32_16x16x32_bf16 v[96:99], v[170:173], v[194:197], v[96:99]
	v_mfma_f32_16x16x32_bf16 v[88:91], v[178:181], v[194:197], v[88:91]
	v_mfma_f32_16x16x32_bf16 v[80:83], v[170:173], v[202:205], v[80:83]
	v_mfma_f32_16x16x32_bf16 v[72:75], v[178:181], v[202:205], v[72:75]
	v_mfma_f32_16x16x32_bf16 v[68:71], v[170:173], v[210:213], v[68:71]
	v_mfma_f32_16x16x32_bf16 v[64:67], v[178:181], v[210:213], v[64:67]
	s_barrier
	s_add_i32 s48, s78, s93
	s_add_i32 m0, s48, 0xffffff80
	ds_read_b128 v[182:185], v159 offset:49152
	ds_read_b128 v[186:189], v159 offset:50176
	ds_read_b128 v[190:193], v159 offset:51200
	ds_read_b128 v[194:197], v159 offset:52224
	ds_read_b128 v[198:201], v159 offset:53248
	ds_read_b128 v[202:205], v159 offset:54272
	ds_read_b128 v[206:209], v159 offset:55296
	ds_read_b128 v[210:213], v159 offset:56320
	global_load_lds_dwordx4 v128, s[46:47] offset:128
	s_add_i32 m0, s48, 0x2000
	s_add_u32 s46, s46, 0x100080
	v_lshl_add_u64 v[214:215], v[216:217], 0, s[18:19]
	s_addc_u32 s47, s47, 0
	s_add_i32 s48, s79, s93
	global_load_lds_dwordx4 v[214:215], off
	s_mov_b32 m0, s48
	s_nop 0
	global_load_lds_dwordx4 v128, s[46:47]
	s_add_i32 m0, s48, 0x2000
	s_nop 0
	global_load_lds_dwordx4 v130, s[46:47]
	v_lshl_add_u64 v[214:215], v[218:219], 0, s[18:19]
	s_mov_b32 m0, s60
	s_nop 0
	global_load_lds_dwordx4 v[214:215], off
	v_lshl_add_u64 v[214:215], v[220:221], 0, s[18:19]
	s_mov_b32 m0, s61
	s_nop 0
	global_load_lds_dwordx4 v[214:215], off
	s_waitcnt vmcnt(8)
	s_waitcnt lgkmcnt(0)
	s_barrier
	s_waitcnt lgkmcnt(0)
	v_mfma_f32_16x16x32_bf16 v[60:63], v[140:143], v[182:185], v[60:63]
	v_mfma_f32_16x16x32_bf16 v[56:59], v[148:151], v[182:185], v[56:59]
	v_mfma_f32_16x16x32_bf16 v[52:55], v[140:143], v[190:193], v[52:55]
	v_mfma_f32_16x16x32_bf16 v[40:43], v[148:151], v[190:193], v[40:43]
	v_mfma_f32_16x16x32_bf16 v[36:39], v[140:143], v[198:201], v[36:39]
	v_mfma_f32_16x16x32_bf16 v[24:27], v[148:151], v[198:201], v[24:27]
	v_mfma_f32_16x16x32_bf16 v[20:23], v[140:143], v[206:209], v[20:23]
	v_mfma_f32_16x16x32_bf16 v[8:11], v[148:151], v[206:209], v[8:11]
	v_mfma_f32_16x16x32_bf16 v[60:63], v[144:147], v[186:189], v[60:63]
	v_mfma_f32_16x16x32_bf16 v[56:59], v[162:165], v[186:189], v[56:59]
	v_mfma_f32_16x16x32_bf16 v[52:55], v[144:147], v[194:197], v[52:55]
	v_mfma_f32_16x16x32_bf16 v[40:43], v[162:165], v[194:197], v[40:43]
	v_mfma_f32_16x16x32_bf16 v[36:39], v[144:147], v[202:205], v[36:39]
	v_mfma_f32_16x16x32_bf16 v[24:27], v[162:165], v[202:205], v[24:27]
	v_mfma_f32_16x16x32_bf16 v[20:23], v[144:147], v[210:213], v[20:23]
	v_mfma_f32_16x16x32_bf16 v[8:11], v[162:165], v[210:213], v[8:11]
	v_mfma_f32_16x16x32_bf16 v[48:51], v[166:169], v[182:185], v[48:51]
	v_mfma_f32_16x16x32_bf16 v[44:47], v[174:177], v[182:185], v[44:47]
	v_mfma_f32_16x16x32_bf16 v[32:35], v[166:169], v[190:193], v[32:35]
	v_mfma_f32_16x16x32_bf16 v[28:31], v[174:177], v[190:193], v[28:31]
	v_mfma_f32_16x16x32_bf16 v[16:19], v[166:169], v[198:201], v[16:19]
	v_mfma_f32_16x16x32_bf16 v[12:15], v[174:177], v[198:201], v[12:15]
	v_mfma_f32_16x16x32_bf16 v[4:7], v[166:169], v[206:209], v[4:7]
	v_mfma_f32_16x16x32_bf16 v[0:3], v[174:177], v[206:209], v[0:3]
	v_mfma_f32_16x16x32_bf16 v[48:51], v[170:173], v[186:189], v[48:51]
	v_mfma_f32_16x16x32_bf16 v[44:47], v[178:181], v[186:189], v[44:47]
	v_mfma_f32_16x16x32_bf16 v[32:35], v[170:173], v[194:197], v[32:35]
	v_mfma_f32_16x16x32_bf16 v[28:31], v[178:181], v[194:197], v[28:31]
	v_mfma_f32_16x16x32_bf16 v[16:19], v[170:173], v[202:205], v[16:19]
	v_mfma_f32_16x16x32_bf16 v[12:15], v[178:181], v[202:205], v[12:15]
	v_mfma_f32_16x16x32_bf16 v[4:7], v[170:173], v[210:213], v[4:7]
	v_mfma_f32_16x16x32_bf16 v[0:3], v[178:181], v[210:213], v[0:3]
	s_barrier
	s_add_u32 s44, s44, 0x100
	s_addc_u32 s45, s45, 0
	s_add_u32 s76, s76, 0x100
	s_addc_u32 s77, s77, 0
	s_cmp_lt_i32 s72, s27
	s_mov_b32 s46, s72
	s_cbranch_scc1 .LBB0_1154
	s_setprio 0
	s_andn2_b64 vcc, exec, s[94:95]
	s_cbranch_vccnz .LBB0_1157
	s_barrier

.LBB0_1296:
	s_ashr_i32 s41, s40, 31
	s_xor_b64 s[58:59], s[58:59], -1
	s_xor_b64 s[52:53], s[64:65], -1
	s_lshl_b64 s[48:49], s[40:41], 20
	s_add_u32 s24, s29, s48
	s_addc_u32 s25, s31, s49
	s_ashr_i32 s45, s44, 31
	s_lshl_b64 s[50:51], s[44:45], 7
	s_add_u32 s48, s24, s50
	s_addc_u32 s49, s25, s51
	s_and_b64 s[96:97], s[64:65], exec
	s_cselect_b32 s41, s61, s49
	s_cselect_b32 s45, s60, s48
	s_ashr_i32 s43, s42, 31
	s_lshl_b64 s[96:97], s[42:43], 20
	s_add_u32 s24, s9, s96
	s_addc_u32 s25, s27, s97
	s_add_u32 s50, s24, s50
	s_addc_u32 s51, s25, s51
	s_and_b64 s[64:65], s[64:65], exec
	s_cselect_b32 s43, s63, s51
	s_cselect_b32 s96, s62, s50
	s_add_i32 s97, s91, -2
	s_add_u32 s60, s60, 0x80080
	s_addc_u32 s61, s61, 0
	s_add_u32 vcc_lo, s62, 0x100
	s_addc_u32 vcc_hi, s63, 0
	s_mov_b32 s62, 0
	v_mov_b32_e32 v0, 0
	v_mov_b32_e32 v1, 0
	v_mov_b32_e32 v2, 0
	v_mov_b32_e32 v3, 0
	v_mov_b32_e32 v4, 0
	v_mov_b32_e32 v5, 0
	v_mov_b32_e32 v6, 0
	v_mov_b32_e32 v7, 0
	v_mov_b32_e32 v8, 0
	v_mov_b32_e32 v9, 0
	v_mov_b32_e32 v10, 0
	v_mov_b32_e32 v11, 0
	v_mov_b32_e32 v12, 0
	v_mov_b32_e32 v13, 0
	v_mov_b32_e32 v14, 0
	v_mov_b32_e32 v15, 0
	v_mov_b32_e32 v16, 0
	v_mov_b32_e32 v17, 0
	v_mov_b32_e32 v18, 0
	v_mov_b32_e32 v19, 0
	v_mov_b32_e32 v20, 0
	v_mov_b32_e32 v21, 0
	v_mov_b32_e32 v22, 0
	v_mov_b32_e32 v23, 0
	v_mov_b32_e32 v24, 0
	v_mov_b32_e32 v25, 0
	v_mov_b32_e32 v26, 0
	v_mov_b32_e32 v27, 0
	v_mov_b32_e32 v28, 0
	v_mov_b32_e32 v29, 0
	v_mov_b32_e32 v30, 0
	v_mov_b32_e32 v31, 0
	v_mov_b32_e32 v32, 0
	v_mov_b32_e32 v33, 0
	v_mov_b32_e32 v34, 0
	v_mov_b32_e32 v35, 0
	v_mov_b32_e32 v36, 0
	v_mov_b32_e32 v37, 0
	v_mov_b32_e32 v38, 0
	v_mov_b32_e32 v39, 0
	v_mov_b32_e32 v40, 0
	v_mov_b32_e32 v41, 0
	v_mov_b32_e32 v42, 0
	v_mov_b32_e32 v43, 0
	v_mov_b32_e32 v44, 0
	v_mov_b32_e32 v45, 0
	v_mov_b32_e32 v46, 0
	v_mov_b32_e32 v47, 0
	v_mov_b32_e32 v48, 0
	v_mov_b32_e32 v49, 0
	v_mov_b32_e32 v50, 0
	v_mov_b32_e32 v51, 0
	v_mov_b32_e32 v52, 0
	v_mov_b32_e32 v53, 0
	v_mov_b32_e32 v54, 0
	v_mov_b32_e32 v55, 0
	v_mov_b32_e32 v56, 0
	v_mov_b32_e32 v57, 0
	v_mov_b32_e32 v58, 0
	v_mov_b32_e32 v59, 0
	v_mov_b32_e32 v60, 0
	v_mov_b32_e32 v61, 0
	v_mov_b32_e32 v62, 0
	v_mov_b32_e32 v63, 0
	v_mov_b32_e32 v64, 0
	v_mov_b32_e32 v65, 0
	v_mov_b32_e32 v66, 0
	v_mov_b32_e32 v67, 0
	v_mov_b32_e32 v68, 0
	v_mov_b32_e32 v69, 0
	v_mov_b32_e32 v70, 0
	v_mov_b32_e32 v71, 0
	v_mov_b32_e32 v72, 0
	v_mov_b32_e32 v73, 0
	v_mov_b32_e32 v74, 0
	v_mov_b32_e32 v75, 0
	v_mov_b32_e32 v76, 0
	v_mov_b32_e32 v77, 0
	v_mov_b32_e32 v78, 0
	v_mov_b32_e32 v79, 0
	v_mov_b32_e32 v84, 0
	v_mov_b32_e32 v85, 0
	v_mov_b32_e32 v86, 0
	v_mov_b32_e32 v87, 0
	v_mov_b32_e32 v92, 0
	v_mov_b32_e32 v93, 0
	v_mov_b32_e32 v94, 0
	v_mov_b32_e32 v95, 0
	v_mov_b32_e32 v100, 0
	v_mov_b32_e32 v101, 0
	v_mov_b32_e32 v102, 0
	v_mov_b32_e32 v103, 0
	v_mov_b32_e32 v108, 0
	v_mov_b32_e32 v109, 0
	v_mov_b32_e32 v110, 0
	v_mov_b32_e32 v111, 0
	v_mov_b32_e32 v80, 0
	v_mov_b32_e32 v81, 0
	v_mov_b32_e32 v82, 0
	v_mov_b32_e32 v83, 0
	v_mov_b32_e32 v88, 0
	v_mov_b32_e32 v89, 0
	v_mov_b32_e32 v90, 0
	v_mov_b32_e32 v91, 0
	v_mov_b32_e32 v96, 0
	v_mov_b32_e32 v97, 0
	v_mov_b32_e32 v98, 0
	v_mov_b32_e32 v99, 0
	v_mov_b32_e32 v104, 0
	v_mov_b32_e32 v105, 0
	v_mov_b32_e32 v106, 0
	v_mov_b32_e32 v107, 0
	v_mov_b32_e32 v112, 0
	v_mov_b32_e32 v113, 0
	v_mov_b32_e32 v114, 0
	v_mov_b32_e32 v115, 0
	v_mov_b32_e32 v116, 0
	v_mov_b32_e32 v117, 0
	v_mov_b32_e32 v118, 0
	v_mov_b32_e32 v119, 0
	v_mov_b32_e32 v120, 0
	v_mov_b32_e32 v121, 0
	v_mov_b32_e32 v122, 0
	v_mov_b32_e32 v123, 0
	v_mov_b32_e32 v124, 0
	v_mov_b32_e32 v125, 0
	v_mov_b32_e32 v126, 0
	v_mov_b32_e32 v127, 0
	v_readlane_b32 s98, v250, 9
	s_nop 1
	s_cmp_lt_u32 s98, 4
	s_cbranch_scc1 .Lprio_skip2
	s_setprio 1
.Lprio_skip2:
.LBB0_1297:
	v_add_u32_e32 v154, s80, v181
	v_add_u32_e32 v170, s81, v181
	ds_read_b128 v[142:145], v154
	ds_read_b128 v[146:149], v154 offset:1024
	ds_read_b128 v[150:153], v154 offset:2048
	ds_read_b128 v[154:157], v154 offset:3072
	ds_read_b128 v[158:161], v170
	ds_read_b128 v[162:165], v170 offset:1024
	ds_read_b128 v[166:169], v170 offset:2048
	ds_read_b128 v[170:173], v170 offset:3072
	s_add_i32 s72, s62, 2
	s_add_u32 s24, s60, 0xfff80080
	s_addc_u32 s25, s61, -1
	s_cmp_eq_u32 s97, s62
	s_cselect_b32 s62, s96, vcc_lo
	s_cselect_b32 s65, s41, s25
	s_cselect_b32 s64, s45, s24
	s_cselect_b32 s63, s43, vcc_hi
	s_add_i32 m0, s55, 0xc000
	ds_read_b128 v[174:177], v183
	ds_read_b128 v[184:187], v183 offset:1024
	ds_read_b128 v[188:191], v183 offset:2048
	ds_read_b128 v[192:195], v183 offset:3072
	ds_read_b128 v[196:199], v183 offset:4096
	ds_read_b128 v[200:203], v183 offset:5120
	ds_read_b128 v[204:207], v183 offset:6144
	ds_read_b128 v[208:211], v183 offset:7168
	global_load_lds_dwordx4 v138, s[60:61]
	s_add_i32 m0, s55, 0xe000
	s_nop 0
	global_load_lds_dwordx4 v140, s[60:61]
	s_waitcnt vmcnt(8)
	s_waitcnt lgkmcnt(0)
	s_barrier
	s_waitcnt lgkmcnt(0)
	v_mfma_i32_16x16x64_i8 v[124:127], v[142:145], v[174:177], v[124:127]
	v_mfma_i32_16x16x64_i8 v[120:123], v[150:153], v[174:177], v[120:123]
	v_mfma_i32_16x16x64_i8 v[116:119], v[142:145], v[188:191], v[116:119]
	v_mfma_i32_16x16x64_i8 v[112:115], v[150:153], v[188:191], v[112:115]
	v_mfma_i32_16x16x64_i8 v[104:107], v[142:145], v[196:199], v[104:107]
	v_mfma_i32_16x16x64_i8 v[96:99], v[150:153], v[196:199], v[96:99]
	v_mfma_i32_16x16x64_i8 v[88:91], v[142:145], v[204:207], v[88:91]
	v_mfma_i32_16x16x64_i8 v[80:83], v[150:153], v[204:207], v[80:83]
	v_mfma_i32_16x16x64_i8 v[124:127], v[146:149], v[184:187], v[124:127]
	v_mfma_i32_16x16x64_i8 v[120:123], v[154:157], v[184:187], v[120:123]
	v_mfma_i32_16x16x64_i8 v[116:119], v[146:149], v[192:195], v[116:119]
	v_mfma_i32_16x16x64_i8 v[112:115], v[154:157], v[192:195], v[112:115]
	v_mfma_i32_16x16x64_i8 v[104:107], v[146:149], v[200:203], v[104:107]
	v_mfma_i32_16x16x64_i8 v[96:99], v[154:157], v[200:203], v[96:99]
	v_mfma_i32_16x16x64_i8 v[88:91], v[146:149], v[208:211], v[88:91]
	v_mfma_i32_16x16x64_i8 v[80:83], v[154:157], v[208:211], v[80:83]
	v_mfma_i32_16x16x64_i8 v[108:111], v[158:161], v[174:177], v[108:111]
	v_mfma_i32_16x16x64_i8 v[100:103], v[166:169], v[174:177], v[100:103]
	v_mfma_i32_16x16x64_i8 v[92:95], v[158:161], v[188:191], v[92:95]
	v_mfma_i32_16x16x64_i8 v[84:87], v[166:169], v[188:191], v[84:87]
	v_mfma_i32_16x16x64_i8 v[76:79], v[158:161], v[196:199], v[76:79]
	v_mfma_i32_16x16x64_i8 v[72:75], v[166:169], v[196:199], v[72:75]
	v_mfma_i32_16x16x64_i8 v[68:71], v[158:161], v[204:207], v[68:71]
	v_mfma_i32_16x16x64_i8 v[64:67], v[166:169], v[204:207], v[64:67]
	v_mfma_i32_16x16x64_i8 v[108:111], v[162:165], v[184:187], v[108:111]
	v_mfma_i32_16x16x64_i8 v[100:103], v[170:173], v[184:187], v[100:103]
	v_mfma_i32_16x16x64_i8 v[92:95], v[162:165], v[192:195], v[92:95]
	v_mfma_i32_16x16x64_i8 v[84:87], v[170:173], v[192:195], v[84:87]
	v_mfma_i32_16x16x64_i8 v[76:79], v[162:165], v[200:203], v[76:79]
	v_mfma_i32_16x16x64_i8 v[72:75], v[170:173], v[200:203], v[72:75]
	v_mfma_i32_16x16x64_i8 v[68:71], v[162:165], v[208:211], v[68:71]
	v_mfma_i32_16x16x64_i8 v[64:67], v[170:173], v[208:211], v[64:67]
	s_barrier
	s_add_i32 s24, s80, s93
	s_mov_b32 m0, s24
	ds_read_b128 v[174:177], v183 offset:16384
	ds_read_b128 v[184:187], v183 offset:17408
	ds_read_b128 v[188:191], v183 offset:18432
	ds_read_b128 v[192:195], v183 offset:19456
	ds_read_b128 v[196:199], v183 offset:20480
	ds_read_b128 v[200:203], v183 offset:21504
	ds_read_b128 v[204:207], v183 offset:22528
	ds_read_b128 v[208:211], v183 offset:23552
	global_load_lds_dwordx4 v130, s[62:63]
	s_add_i32 m0, s24, 0x2000
	s_add_u32 s24, s62, 0x80000
	v_lshl_add_u64 v[212:213], s[62:63], 0, v[134:135]
	s_addc_u32 s25, s63, 0
	s_add_i32 s73, s81, s93
	global_load_lds_dwordx4 v134, s[62:63]
	s_mov_b32 m0, s73
	s_nop 0
	global_load_lds_dwordx4 v130, s[24:25]
	s_add_i32 m0, s73, 0x2000
	s_nop 0
	global_load_lds_dwordx4 v134, s[24:25]
	s_mov_b32 m0, s55
	s_nop 0
	global_load_lds_dwordx4 v128, s[64:65]
	s_mov_b32 m0, s57
	s_nop 0
	global_load_lds_dwordx4 v132, s[64:65]
	s_waitcnt vmcnt(8)
	s_waitcnt lgkmcnt(0)
	s_barrier
	s_waitcnt lgkmcnt(0)
	v_mfma_i32_16x16x64_i8 v[60:63], v[142:145], v[174:177], v[60:63]
	v_mfma_i32_16x16x64_i8 v[56:59], v[150:153], v[174:177], v[56:59]
	v_mfma_i32_16x16x64_i8 v[52:55], v[142:145], v[188:191], v[52:55]
	v_mfma_i32_16x16x64_i8 v[48:51], v[150:153], v[188:191], v[48:51]
	v_mfma_i32_16x16x64_i8 v[44:47], v[142:145], v[196:199], v[44:47]
	v_mfma_i32_16x16x64_i8 v[40:43], v[150:153], v[196:199], v[40:43]
	v_mfma_i32_16x16x64_i8 v[36:39], v[142:145], v[204:207], v[36:39]
	v_mfma_i32_16x16x64_i8 v[32:35], v[150:153], v[204:207], v[32:35]
	v_mfma_i32_16x16x64_i8 v[60:63], v[146:149], v[184:187], v[60:63]
	v_mfma_i32_16x16x64_i8 v[56:59], v[154:157], v[184:187], v[56:59]
	v_mfma_i32_16x16x64_i8 v[52:55], v[146:149], v[192:195], v[52:55]
	v_mfma_i32_16x16x64_i8 v[48:51], v[154:157], v[192:195], v[48:51]
	v_mfma_i32_16x16x64_i8 v[44:47], v[146:149], v[200:203], v[44:47]
	v_mfma_i32_16x16x64_i8 v[40:43], v[154:157], v[200:203], v[40:43]
	v_mfma_i32_16x16x64_i8 v[36:39], v[146:149], v[208:211], v[36:39]
	v_mfma_i32_16x16x64_i8 v[32:35], v[154:157], v[208:211], v[32:35]
	v_mfma_i32_16x16x64_i8 v[28:31], v[158:161], v[174:177], v[28:31]
	v_mfma_i32_16x16x64_i8 v[24:27], v[166:169], v[174:177], v[24:27]
	v_mfma_i32_16x16x64_i8 v[20:23], v[158:161], v[188:191], v[20:23]
	v_mfma_i32_16x16x64_i8 v[16:19], v[166:169], v[188:191], v[16:19]
	v_mfma_i32_16x16x64_i8 v[12:15], v[158:161], v[196:199], v[12:15]
	v_mfma_i32_16x16x64_i8 v[8:11], v[166:169], v[196:199], v[8:11]
	v_mfma_i32_16x16x64_i8 v[4:7], v[158:161], v[204:207], v[4:7]
	v_mfma_i32_16x16x64_i8 v[0:3], v[166:169], v[204:207], v[0:3]
	v_mfma_i32_16x16x64_i8 v[28:31], v[162:165], v[184:187], v[28:31]
	v_mfma_i32_16x16x64_i8 v[24:27], v[170:173], v[184:187], v[24:27]
	v_mfma_i32_16x16x64_i8 v[20:23], v[162:165], v[192:195], v[20:23]
	v_mfma_i32_16x16x64_i8 v[16:19], v[170:173], v[192:195], v[16:19]
	v_mfma_i32_16x16x64_i8 v[12:15], v[162:165], v[200:203], v[12:15]
	v_mfma_i32_16x16x64_i8 v[8:11], v[170:173], v[200:203], v[8:11]
	v_mfma_i32_16x16x64_i8 v[4:7], v[162:165], v[208:211], v[4:7]
	v_mfma_i32_16x16x64_i8 v[0:3], v[170:173], v[208:211], v[0:3]
	s_barrier
	s_add_i32 s73, 0, 0x18000
	s_add_i32 s66, 0, 0x1c000
	v_add_u32_e32 v154, s73, v181
	v_add_u32_e32 v170, s66, v181
	ds_read_b128 v[142:145], v154
	ds_read_b128 v[146:149], v154 offset:1024
	ds_read_b128 v[150:153], v154 offset:2048
	ds_read_b128 v[154:157], v154 offset:3072
	ds_read_b128 v[158:161], v170
	ds_read_b128 v[162:165], v170 offset:1024
	ds_read_b128 v[166:169], v170 offset:2048
	ds_read_b128 v[170:173], v170 offset:3072
	s_add_u32 s24, s64, 0x80000
	s_addc_u32 s25, s65, 0
	s_mov_b32 m0, s69
	ds_read_b128 v[174:177], v183 offset:32768
	ds_read_b128 v[184:187], v183 offset:33792
	ds_read_b128 v[188:191], v183 offset:34816
	ds_read_b128 v[192:195], v183 offset:35840
	ds_read_b128 v[196:199], v183 offset:36864
	ds_read_b128 v[200:203], v183 offset:37888
	ds_read_b128 v[204:207], v183 offset:38912
	ds_read_b128 v[208:211], v183 offset:39936
	global_load_lds_dwordx4 v128, s[24:25]
	s_mov_b32 m0, s74
	s_nop 0
	global_load_lds_dwordx4 v132, s[24:25]
	s_waitcnt vmcnt(8)
	s_waitcnt lgkmcnt(0)
	s_barrier
	s_waitcnt lgkmcnt(0)
	v_mfma_i32_16x16x64_i8 v[124:127], v[142:145], v[174:177], v[124:127]
	v_mfma_i32_16x16x64_i8 v[120:123], v[150:153], v[174:177], v[120:123]
	v_mfma_i32_16x16x64_i8 v[116:119], v[142:145], v[188:191], v[116:119]
	v_mfma_i32_16x16x64_i8 v[112:115], v[150:153], v[188:191], v[112:115]
	v_mfma_i32_16x16x64_i8 v[104:107], v[142:145], v[196:199], v[104:107]
	v_mfma_i32_16x16x64_i8 v[96:99], v[150:153], v[196:199], v[96:99]
	v_mfma_i32_16x16x64_i8 v[88:91], v[142:145], v[204:207], v[88:91]
	v_mfma_i32_16x16x64_i8 v[80:83], v[150:153], v[204:207], v[80:83]
	v_mfma_i32_16x16x64_i8 v[124:127], v[146:149], v[184:187], v[124:127]
	v_mfma_i32_16x16x64_i8 v[120:123], v[154:157], v[184:187], v[120:123]
	v_mfma_i32_16x16x64_i8 v[116:119], v[146:149], v[192:195], v[116:119]
	v_mfma_i32_16x16x64_i8 v[112:115], v[154:157], v[192:195], v[112:115]
	v_mfma_i32_16x16x64_i8 v[104:107], v[146:149], v[200:203], v[104:107]
	v_mfma_i32_16x16x64_i8 v[96:99], v[154:157], v[200:203], v[96:99]
	v_mfma_i32_16x16x64_i8 v[88:91], v[146:149], v[208:211], v[88:91]
	v_mfma_i32_16x16x64_i8 v[80:83], v[154:157], v[208:211], v[80:83]
	v_mfma_i32_16x16x64_i8 v[108:111], v[158:161], v[174:177], v[108:111]
	v_mfma_i32_16x16x64_i8 v[100:103], v[166:169], v[174:177], v[100:103]
	v_mfma_i32_16x16x64_i8 v[92:95], v[158:161], v[188:191], v[92:95]
	v_mfma_i32_16x16x64_i8 v[84:87], v[166:169], v[188:191], v[84:87]
	v_mfma_i32_16x16x64_i8 v[76:79], v[158:161], v[196:199], v[76:79]
	v_mfma_i32_16x16x64_i8 v[72:75], v[166:169], v[196:199], v[72:75]
	v_mfma_i32_16x16x64_i8 v[68:71], v[158:161], v[204:207], v[68:71]
	v_mfma_i32_16x16x64_i8 v[64:67], v[166:169], v[204:207], v[64:67]
	v_mfma_i32_16x16x64_i8 v[108:111], v[162:165], v[184:187], v[108:111]
	v_mfma_i32_16x16x64_i8 v[100:103], v[170:173], v[184:187], v[100:103]
	v_mfma_i32_16x16x64_i8 v[92:95], v[162:165], v[192:195], v[92:95]
	v_mfma_i32_16x16x64_i8 v[84:87], v[170:173], v[192:195], v[84:87]
	v_mfma_i32_16x16x64_i8 v[76:79], v[162:165], v[200:203], v[76:79]
	v_mfma_i32_16x16x64_i8 v[72:75], v[170:173], v[200:203], v[72:75]
	v_mfma_i32_16x16x64_i8 v[68:71], v[162:165], v[208:211], v[68:71]
	v_mfma_i32_16x16x64_i8 v[64:67], v[170:173], v[208:211], v[64:67]
	s_barrier
	s_add_i32 s24, s73, s93
	s_add_i32 m0, s24, 0xffffff80
	ds_read_b128 v[174:177], v183 offset:49152
	ds_read_b128 v[184:187], v183 offset:50176
	ds_read_b128 v[188:191], v183 offset:51200
	ds_read_b128 v[192:195], v183 offset:52224
	ds_read_b128 v[196:199], v183 offset:53248
	ds_read_b128 v[200:203], v183 offset:54272
	ds_read_b128 v[204:207], v183 offset:55296
	ds_read_b128 v[208:211], v183 offset:56320
	global_load_lds_dwordx4 v130, s[62:63] offset:128
	s_add_i32 m0, s24, 0x2000
	s_add_u32 s24, s62, 0x80080
	v_lshl_add_u64 v[178:179], v[212:213], 0, s[38:39]
	s_addc_u32 s25, s63, 0
	s_add_i32 s62, s66, s93
	global_load_lds_dwordx4 v[178:179], off
	s_mov_b32 m0, s62
	s_nop 0
	global_load_lds_dwordx4 v130, s[24:25]
	s_add_i32 m0, s62, 0x2000
	s_nop 0
	global_load_lds_dwordx4 v134, s[24:25]
	s_add_i32 m0, s77, 0xffffff80
	s_nop 0
	global_load_lds_dwordx4 v128, s[64:65] offset:128
	s_add_i32 m0, s78, 0xffffff80
	s_nop 0
	global_load_lds_dwordx4 v132, s[64:65] offset:128
	s_waitcnt vmcnt(8)
	s_waitcnt lgkmcnt(0)
	s_barrier
	s_waitcnt lgkmcnt(0)
	v_mfma_i32_16x16x64_i8 v[60:63], v[142:145], v[174:177], v[60:63]
	v_mfma_i32_16x16x64_i8 v[56:59], v[150:153], v[174:177], v[56:59]
	v_mfma_i32_16x16x64_i8 v[52:55], v[142:145], v[188:191], v[52:55]
	v_mfma_i32_16x16x64_i8 v[48:51], v[150:153], v[188:191], v[48:51]
	v_mfma_i32_16x16x64_i8 v[44:47], v[142:145], v[196:199], v[44:47]
	v_mfma_i32_16x16x64_i8 v[40:43], v[150:153], v[196:199], v[40:43]
	v_mfma_i32_16x16x64_i8 v[36:39], v[142:145], v[204:207], v[36:39]
	v_mfma_i32_16x16x64_i8 v[32:35], v[150:153], v[204:207], v[32:35]
	v_mfma_i32_16x16x64_i8 v[60:63], v[146:149], v[184:187], v[60:63]
	v_mfma_i32_16x16x64_i8 v[56:59], v[154:157], v[184:187], v[56:59]
	v_mfma_i32_16x16x64_i8 v[52:55], v[146:149], v[192:195], v[52:55]
	v_mfma_i32_16x16x64_i8 v[48:51], v[154:157], v[192:195], v[48:51]
	v_mfma_i32_16x16x64_i8 v[44:47], v[146:149], v[200:203], v[44:47]
	v_mfma_i32_16x16x64_i8 v[40:43], v[154:157], v[200:203], v[40:43]
	v_mfma_i32_16x16x64_i8 v[36:39], v[146:149], v[208:211], v[36:39]
	v_mfma_i32_16x16x64_i8 v[32:35], v[154:157], v[208:211], v[32:35]
	v_mfma_i32_16x16x64_i8 v[28:31], v[158:161], v[174:177], v[28:31]
	v_mfma_i32_16x16x64_i8 v[24:27], v[166:169], v[174:177], v[24:27]
	v_mfma_i32_16x16x64_i8 v[20:23], v[158:161], v[188:191], v[20:23]
	v_mfma_i32_16x16x64_i8 v[16:19], v[166:169], v[188:191], v[16:19]
	v_mfma_i32_16x16x64_i8 v[12:15], v[158:161], v[196:199], v[12:15]
	v_mfma_i32_16x16x64_i8 v[8:11], v[166:169], v[196:199], v[8:11]
	v_mfma_i32_16x16x64_i8 v[4:7], v[158:161], v[204:207], v[4:7]
	v_mfma_i32_16x16x64_i8 v[0:3], v[166:169], v[204:207], v[0:3]
	v_mfma_i32_16x16x64_i8 v[28:31], v[162:165], v[184:187], v[28:31]
	v_mfma_i32_16x16x64_i8 v[24:27], v[170:173], v[184:187], v[24:27]
	v_mfma_i32_16x16x64_i8 v[20:23], v[162:165], v[192:195], v[20:23]
	v_mfma_i32_16x16x64_i8 v[16:19], v[170:173], v[192:195], v[16:19]
	v_mfma_i32_16x16x64_i8 v[12:15], v[162:165], v[200:203], v[12:15]
	v_mfma_i32_16x16x64_i8 v[8:11], v[170:173], v[200:203], v[8:11]
	v_mfma_i32_16x16x64_i8 v[4:7], v[162:165], v[208:211], v[4:7]
	v_mfma_i32_16x16x64_i8 v[0:3], v[170:173], v[208:211], v[0:3]
	s_barrier
	s_add_u32 s60, s60, 0x100
	s_addc_u32 s61, s61, 0
	s_add_u32 vcc_lo, vcc_lo, 0x100
	s_addc_u32 vcc_hi, vcc_hi, 0
	s_cmp_ge_i32 s72, s91
	s_mov_b32 s62, s72
	s_cbranch_scc0 .LBB0_1297
	s_setprio 0
	s_andn2_b64 vcc, exec, s[58:59]
	s_cbranch_vccnz .LBB0_1311
	global_load_dword v142, v131, s[10:11] sc1
	s_waitcnt vmcnt(0)
	v_cmp_lt_u32_e32 vcc, s7, v142
	s_cbranch_vccnz .LBB0_1310
	s_mov_b32 s41, 0x3ffff8
	s_branch .LBB0_1302

.LBB0_1443:
	s_add_i32 s53, s96, -2
	s_add_u32 s97, s60, 0x100
	v_mov_b32_e32 v32, 0
	s_addc_u32 vcc_lo, s61, 0
	s_mov_b32 s62, 0
	v_mov_b32_e32 v33, v32
	v_mov_b32_e32 v34, v32
	v_mov_b32_e32 v35, v32
	v_mov_b32_e32 v36, v32
	v_mov_b32_e32 v37, v32
	v_mov_b32_e32 v38, v32
	v_mov_b32_e32 v39, v32
	v_mov_b32_e32 v44, v32
	v_mov_b32_e32 v45, v32
	v_mov_b32_e32 v46, v32
	v_mov_b32_e32 v47, v32
	v_mov_b32_e32 v48, v32
	v_mov_b32_e32 v49, v32
	v_mov_b32_e32 v50, v32
	v_mov_b32_e32 v51, v32
	v_mov_b32_e32 v60, v32
	v_mov_b32_e32 v61, v32
	v_mov_b32_e32 v62, v32
	v_mov_b32_e32 v63, v32
	v_mov_b32_e32 v64, v32
	v_mov_b32_e32 v65, v32
	v_mov_b32_e32 v66, v32
	v_mov_b32_e32 v67, v32
	v_mov_b32_e32 v76, v32
	v_mov_b32_e32 v77, v32
	v_mov_b32_e32 v78, v32
	v_mov_b32_e32 v79, v32
	v_mov_b32_e32 v80, v32
	v_mov_b32_e32 v81, v32
	v_mov_b32_e32 v82, v32
	v_mov_b32_e32 v83, v32
	v_mov_b32_e32 v40, v32
	v_mov_b32_e32 v41, v32
	v_mov_b32_e32 v42, v32
	v_mov_b32_e32 v43, v32
	v_mov_b32_e32 v52, v32
	v_mov_b32_e32 v53, v32
	v_mov_b32_e32 v54, v32
	v_mov_b32_e32 v55, v32
	v_mov_b32_e32 v56, v32
	v_mov_b32_e32 v57, v32
	v_mov_b32_e32 v58, v32
	v_mov_b32_e32 v59, v32
	v_mov_b32_e32 v68, v32
	v_mov_b32_e32 v69, v32
	v_mov_b32_e32 v70, v32
	v_mov_b32_e32 v71, v32
	v_mov_b32_e32 v72, v32
	v_mov_b32_e32 v73, v32
	v_mov_b32_e32 v74, v32
	v_mov_b32_e32 v75, v32
	v_mov_b32_e32 v84, v32
	v_mov_b32_e32 v85, v32
	v_mov_b32_e32 v86, v32
	v_mov_b32_e32 v87, v32
	v_mov_b32_e32 v88, v32
	v_mov_b32_e32 v89, v32
	v_mov_b32_e32 v90, v32
	v_mov_b32_e32 v91, v32
	v_mov_b32_e32 v92, v32
	v_mov_b32_e32 v93, v32
	v_mov_b32_e32 v94, v32
	v_mov_b32_e32 v95, v32
	v_mov_b32_e32 v96, v32
	v_mov_b32_e32 v97, v32
	v_mov_b32_e32 v98, v32
	v_mov_b32_e32 v99, v32
	v_mov_b32_e32 v100, v32
	v_mov_b32_e32 v101, v32
	v_mov_b32_e32 v102, v32
	v_mov_b32_e32 v103, v32
	v_mov_b32_e32 v104, v32
	v_mov_b32_e32 v105, v32
	v_mov_b32_e32 v106, v32
	v_mov_b32_e32 v107, v32
	v_mov_b32_e32 v112, v32
	v_mov_b32_e32 v113, v32
	v_mov_b32_e32 v114, v32
	v_mov_b32_e32 v115, v32
	v_mov_b32_e32 v120, v32
	v_mov_b32_e32 v121, v32
	v_mov_b32_e32 v122, v32
	v_mov_b32_e32 v123, v32
	v_mov_b32_e32 v128, v32
	v_mov_b32_e32 v129, v32
	v_mov_b32_e32 v130, v32
	v_mov_b32_e32 v131, v32
	v_mov_b32_e32 v136, v32
	v_mov_b32_e32 v137, v32
	v_mov_b32_e32 v138, v32
	v_mov_b32_e32 v139, v32
	v_mov_b32_e32 v144, v32
	v_mov_b32_e32 v145, v32
	v_mov_b32_e32 v146, v32
	v_mov_b32_e32 v147, v32
	v_mov_b32_e32 v108, v32
	v_mov_b32_e32 v109, v32
	v_mov_b32_e32 v110, v32
	v_mov_b32_e32 v111, v32
	v_mov_b32_e32 v116, v32
	v_mov_b32_e32 v117, v32
	v_mov_b32_e32 v118, v32
	v_mov_b32_e32 v119, v32
	v_mov_b32_e32 v124, v32
	v_mov_b32_e32 v125, v32
	v_mov_b32_e32 v126, v32
	v_mov_b32_e32 v127, v32
	v_mov_b32_e32 v132, v32
	v_mov_b32_e32 v133, v32
	v_mov_b32_e32 v134, v32
	v_mov_b32_e32 v135, v32
	v_mov_b32_e32 v140, v32
	v_mov_b32_e32 v141, v32
	v_mov_b32_e32 v142, v32
	v_mov_b32_e32 v143, v32
	v_mov_b32_e32 v148, v32
	v_mov_b32_e32 v149, v32
	v_mov_b32_e32 v150, v32
	v_mov_b32_e32 v151, v32
	v_mov_b32_e32 v152, v32
	v_mov_b32_e32 v153, v32
	v_mov_b32_e32 v154, v32
	v_mov_b32_e32 v155, v32
	v_mov_b32_e32 v156, v32
	v_mov_b32_e32 v157, v32
	v_mov_b32_e32 v158, v32
	v_mov_b32_e32 v159, v32
	v_readlane_b32 s98, v250, 9
	s_nop 1
	s_cmp_lt_u32 s98, 4
	s_cbranch_scc1 .Lprio_skip3
	s_setprio 1
.Lprio_skip3:
.LBB0_1444:
	ds_read_b128 v[24:27], v191
	ds_read_b128 v[28:31], v191 offset:1024
	ds_read_b128 v[16:19], v191 offset:2048
	ds_read_b128 v[20:23], v191 offset:3072
	ds_read_b128 v[8:11], v192
	ds_read_b128 v[12:15], v192 offset:1024
	s_waitcnt lgkmcnt(0)
	ds_read_b128 v[0:3], v192 offset:2048
	ds_read_b128 v[4:7], v192 offset:3072
	s_add_i32 vcc_hi, s62, 2
	s_add_u32 s60, s58, 0x100
	s_addc_u32 s61, s59, 0
	s_cmp_eq_u32 s53, s62
	s_cselect_b32 s62, s56, s97
	s_cselect_b32 s65, s55, s61
	s_cselect_b32 s64, s54, s60
	s_cselect_b32 s63, s57, vcc_lo
	s_add_i32 m0, s31, 0xc000
	ds_read_b128 v[172:175], v193
	ds_read_b128 v[176:179], v193 offset:1024
	ds_read_b128 v[194:197], v193 offset:2048
	ds_read_b128 v[198:201], v193 offset:3072
	ds_read_b128 v[202:205], v193 offset:4096
	ds_read_b128 v[206:209], v193 offset:5120
	ds_read_b128 v[210:213], v193 offset:6144
	ds_read_b128 v[214:217], v193 offset:7168
	global_load_lds_dwordx4 v166, s[58:59]
	s_add_i32 m0, s31, 0xe000
	s_nop 0
	global_load_lds_dwordx4 v168, s[58:59]
	s_waitcnt vmcnt(8)
	s_waitcnt lgkmcnt(0)
	s_barrier
	s_waitcnt lgkmcnt(0)
	v_mfma_f32_16x16x128_f8f6f4 v[156:159], v[24:31], v[172:179], v[156:159]
	v_mfma_f32_16x16x128_f8f6f4 v[152:155], v[16:23], v[172:179], v[152:155]
	v_mfma_f32_16x16x128_f8f6f4 v[148:151], v[24:31], v[194:201], v[148:151]
	v_mfma_f32_16x16x128_f8f6f4 v[140:143], v[16:23], v[194:201], v[140:143]
	v_mfma_f32_16x16x128_f8f6f4 v[132:135], v[24:31], v[202:209], v[132:135]
	v_mfma_f32_16x16x128_f8f6f4 v[124:127], v[16:23], v[202:209], v[124:127]
	v_mfma_f32_16x16x128_f8f6f4 v[116:119], v[24:31], v[210:217], v[116:119]
	v_mfma_f32_16x16x128_f8f6f4 v[108:111], v[16:23], v[210:217], v[108:111]
	v_mfma_f32_16x16x128_f8f6f4 v[144:147], v[8:15], v[172:179], v[144:147]
	v_mfma_f32_16x16x128_f8f6f4 v[136:139], v[0:7], v[172:179], v[136:139]
	v_mfma_f32_16x16x128_f8f6f4 v[128:131], v[8:15], v[194:201], v[128:131]
	v_mfma_f32_16x16x128_f8f6f4 v[120:123], v[0:7], v[194:201], v[120:123]
	v_mfma_f32_16x16x128_f8f6f4 v[112:115], v[8:15], v[202:209], v[112:115]
	v_mfma_f32_16x16x128_f8f6f4 v[104:107], v[0:7], v[202:209], v[104:107]
	v_mfma_f32_16x16x128_f8f6f4 v[100:103], v[8:15], v[210:217], v[100:103]
	v_mfma_f32_16x16x128_f8f6f4 v[96:99], v[0:7], v[210:217], v[96:99]
	s_barrier
	s_add_i32 s24, s82, s93
	s_mov_b32 m0, s24
	ds_read_b128 v[194:197], v193 offset:16384
	ds_read_b128 v[198:201], v193 offset:17408
	ds_read_b128 v[202:205], v193 offset:18432
	ds_read_b128 v[206:209], v193 offset:19456
	ds_read_b128 v[210:213], v193 offset:20480
	ds_read_b128 v[214:217], v193 offset:21504
	ds_read_b128 v[218:221], v193 offset:22528
	ds_read_b128 v[222:225], v193 offset:23552
	global_load_lds_dwordx4 v160, s[62:63]
	s_add_i32 m0, s24, 0x2000
	s_add_u32 s24, s62, 0x158000
	s_addc_u32 s25, s63, 0
	s_add_i32 s58, s83, s93
	global_load_lds_dwordx4 v162, s[62:63]
	s_mov_b32 m0, s58
	s_nop 0
	global_load_lds_dwordx4 v160, s[24:25]
	s_add_i32 m0, s58, 0x2000
	s_nop 0
	global_load_lds_dwordx4 v162, s[24:25]
	s_mov_b32 m0, s31
	s_nop 0
	global_load_lds_dwordx4 v160, s[64:65]
	s_mov_b32 m0, s47
	s_nop 0
	global_load_lds_dwordx4 v162, s[64:65]
	s_waitcnt vmcnt(8)
	s_waitcnt lgkmcnt(0)
	s_barrier
	s_waitcnt lgkmcnt(0)
	v_mfma_f32_16x16x128_f8f6f4 v[92:95], v[24:31], v[194:201], v[92:95]
	v_mfma_f32_16x16x128_f8f6f4 v[88:91], v[16:23], v[194:201], v[88:91]
	v_mfma_f32_16x16x128_f8f6f4 v[84:87], v[24:31], v[202:209], v[84:87]
	v_mfma_f32_16x16x128_f8f6f4 v[72:75], v[16:23], v[202:209], v[72:75]
	v_mfma_f32_16x16x128_f8f6f4 v[68:71], v[24:31], v[210:217], v[68:71]
	v_mfma_f32_16x16x128_f8f6f4 v[56:59], v[16:23], v[210:217], v[56:59]
	v_mfma_f32_16x16x128_f8f6f4 v[52:55], v[24:31], v[218:225], v[52:55]
	v_mfma_f32_16x16x128_f8f6f4 v[40:43], v[16:23], v[218:225], v[40:43]
	v_mfma_f32_16x16x128_f8f6f4 v[80:83], v[8:15], v[194:201], v[80:83]
	v_mfma_f32_16x16x128_f8f6f4 v[76:79], v[0:7], v[194:201], v[76:79]
	v_mfma_f32_16x16x128_f8f6f4 v[64:67], v[8:15], v[202:209], v[64:67]
	v_mfma_f32_16x16x128_f8f6f4 v[60:63], v[0:7], v[202:209], v[60:63]
	v_mfma_f32_16x16x128_f8f6f4 v[48:51], v[8:15], v[210:217], v[48:51]
	v_mfma_f32_16x16x128_f8f6f4 v[44:47], v[0:7], v[210:217], v[44:47]
	v_mfma_f32_16x16x128_f8f6f4 v[36:39], v[8:15], v[218:225], v[36:39]
	v_mfma_f32_16x16x128_f8f6f4 v[32:35], v[0:7], v[218:225], v[32:35]
	s_barrier
	s_add_i32 s58, 0, 0x18000
	s_add_i32 s59, 0, 0x1c000
	v_add_u32_e32 v12, s58, v187
	v_add_u32_e32 v28, s59, v187
	ds_read_b128 v[0:3], v12
	ds_read_b128 v[4:7], v12 offset:1024
	ds_read_b128 v[8:11], v12 offset:2048
	ds_read_b128 v[12:15], v12 offset:3072
	ds_read_b128 v[16:19], v28
	ds_read_b128 v[20:23], v28 offset:1024
	ds_read_b128 v[24:27], v28 offset:2048
	ds_read_b128 v[28:31], v28 offset:3072
	s_add_u32 s24, s64, 0x158000
	s_addc_u32 s25, s65, 0
	s_mov_b32 m0, s49
	ds_read_b128 v[194:197], v193 offset:32768
	ds_read_b128 v[198:201], v193 offset:33792
	ds_read_b128 v[202:205], v193 offset:34816
	ds_read_b128 v[206:209], v193 offset:35840
	ds_read_b128 v[210:213], v193 offset:36864
	ds_read_b128 v[214:217], v193 offset:37888
	ds_read_b128 v[218:221], v193 offset:38912
	ds_read_b128 v[222:225], v193 offset:39936
	global_load_lds_dwordx4 v160, s[24:25]
	s_mov_b32 m0, s69
	s_nop 0
	global_load_lds_dwordx4 v162, s[24:25]
	s_waitcnt vmcnt(8)
	s_waitcnt lgkmcnt(0)
	s_barrier
	s_waitcnt lgkmcnt(0)
	v_mfma_f32_16x16x128_f8f6f4 v[156:159], v[0:7], v[194:201], v[156:159]
	v_mfma_f32_16x16x128_f8f6f4 v[152:155], v[8:15], v[194:201], v[152:155]
	v_mfma_f32_16x16x128_f8f6f4 v[148:151], v[0:7], v[202:209], v[148:151]
	v_mfma_f32_16x16x128_f8f6f4 v[140:143], v[8:15], v[202:209], v[140:143]
	v_mfma_f32_16x16x128_f8f6f4 v[132:135], v[0:7], v[210:217], v[132:135]
	v_mfma_f32_16x16x128_f8f6f4 v[124:127], v[8:15], v[210:217], v[124:127]
	v_mfma_f32_16x16x128_f8f6f4 v[116:119], v[0:7], v[218:225], v[116:119]
	v_mfma_f32_16x16x128_f8f6f4 v[108:111], v[8:15], v[218:225], v[108:111]
	v_mfma_f32_16x16x128_f8f6f4 v[144:147], v[16:23], v[194:201], v[144:147]
	v_mfma_f32_16x16x128_f8f6f4 v[136:139], v[24:31], v[194:201], v[136:139]
	v_mfma_f32_16x16x128_f8f6f4 v[128:131], v[16:23], v[202:209], v[128:131]
	v_mfma_f32_16x16x128_f8f6f4 v[120:123], v[24:31], v[202:209], v[120:123]
	v_mfma_f32_16x16x128_f8f6f4 v[112:115], v[16:23], v[210:217], v[112:115]
	v_mfma_f32_16x16x128_f8f6f4 v[104:107], v[24:31], v[210:217], v[104:107]
	v_mfma_f32_16x16x128_f8f6f4 v[100:103], v[16:23], v[218:225], v[100:103]
	v_mfma_f32_16x16x128_f8f6f4 v[96:99], v[24:31], v[218:225], v[96:99]
	s_barrier
	s_add_i32 s24, s58, s93
	s_add_i32 m0, s24, 0xffffff80
	ds_read_b128 v[194:197], v193 offset:49152
	ds_read_b128 v[198:201], v193 offset:50176
	ds_read_b128 v[202:205], v193 offset:51200
	ds_read_b128 v[206:209], v193 offset:52224
	ds_read_b128 v[210:213], v193 offset:53248
	ds_read_b128 v[214:217], v193 offset:54272
	ds_read_b128 v[218:221], v193 offset:55296
	ds_read_b128 v[222:225], v193 offset:56320
	global_load_lds_dwordx4 v160, s[62:63] offset:128
	s_add_i32 m0, s24, 0x1f80
	s_add_u32 s24, s62, 0x158080
	s_addc_u32 s25, s63, 0
	s_add_i32 s58, s59, s93
	global_load_lds_dwordx4 v162, s[62:63] offset:128
	s_mov_b32 m0, s58
	s_nop 0
	global_load_lds_dwordx4 v160, s[24:25]
	s_add_i32 m0, s58, 0x2000
	s_nop 0
	global_load_lds_dwordx4 v162, s[24:25]
	s_add_i32 m0, s79, 0xffffff80
	s_nop 0
	global_load_lds_dwordx4 v160, s[64:65] offset:128
	s_add_i32 m0, s80, 0xffffff80
	s_nop 0
	global_load_lds_dwordx4 v162, s[64:65] offset:128
	s_waitcnt vmcnt(8)
	s_waitcnt lgkmcnt(0)
	s_barrier
	s_waitcnt lgkmcnt(0)
	v_mfma_f32_16x16x128_f8f6f4 v[92:95], v[0:7], v[194:201], v[92:95]
	v_mfma_f32_16x16x128_f8f6f4 v[88:91], v[8:15], v[194:201], v[88:91]
	v_mfma_f32_16x16x128_f8f6f4 v[84:87], v[0:7], v[202:209], v[84:87]
	v_mfma_f32_16x16x128_f8f6f4 v[72:75], v[8:15], v[202:209], v[72:75]
	v_mfma_f32_16x16x128_f8f6f4 v[68:71], v[0:7], v[210:217], v[68:71]
	v_mfma_f32_16x16x128_f8f6f4 v[56:59], v[8:15], v[210:217], v[56:59]
	v_mfma_f32_16x16x128_f8f6f4 v[52:55], v[0:7], v[218:225], v[52:55]
	v_mfma_f32_16x16x128_f8f6f4 v[40:43], v[8:15], v[218:225], v[40:43]
	v_mfma_f32_16x16x128_f8f6f4 v[80:83], v[16:23], v[194:201], v[80:83]
	v_mfma_f32_16x16x128_f8f6f4 v[76:79], v[24:31], v[194:201], v[76:79]
	v_mfma_f32_16x16x128_f8f6f4 v[64:67], v[16:23], v[202:209], v[64:67]
	v_mfma_f32_16x16x128_f8f6f4 v[60:63], v[24:31], v[202:209], v[60:63]
	v_mfma_f32_16x16x128_f8f6f4 v[48:51], v[16:23], v[210:217], v[48:51]
	v_mfma_f32_16x16x128_f8f6f4 v[44:47], v[24:31], v[210:217], v[44:47]
	v_mfma_f32_16x16x128_f8f6f4 v[36:39], v[16:23], v[218:225], v[36:39]
	v_mfma_f32_16x16x128_f8f6f4 v[32:35], v[24:31], v[218:225], v[32:35]
	s_barrier
	s_add_u32 s97, s97, 0x100
	s_addc_u32 vcc_lo, vcc_lo, 0
	s_cmp_ge_i32 vcc_hi, s96
	s_mov_b64 s[58:59], s[60:61]
	s_mov_b32 s62, vcc_hi
	s_cbranch_scc0 .LBB0_1444
	s_setprio 0
	s_nop 15
	s_nop 15
	s_and_b64 vcc, exec, s[94:95]
	s_cbranch_vccz .LBB0_1447
	s_barrier

.LBB0_1587:
	s_ashr_i32 s31, s30, 31
	s_xor_b64 s[48:49], s[48:49], -1
	s_xor_b64 s[42:43], s[54:55], -1
	s_lshl_b64 s[38:39], s[30:31], 20
	s_add_u32 s31, s56, s38
	s_addc_u32 s35, s57, s39
	s_ashr_i32 s37, s36, 31
	s_lshl_b64 s[40:41], s[36:37], 7
	s_add_u32 s38, s31, s40
	s_addc_u32 s39, s35, s41
	s_and_b64 s[76:77], s[54:55], exec
	s_cselect_b32 s31, s51, s39
	s_cselect_b32 s37, s50, s38
	s_ashr_i32 s35, s34, 31
	s_lshl_b64 s[76:77], s[34:35], 20
	s_add_u32 s35, s3, s76
	s_addc_u32 s75, s27, s77
	s_add_u32 s40, s35, s40
	s_addc_u32 s41, s75, s41
	s_and_b64 s[54:55], s[54:55], exec
	s_cselect_b32 s35, s53, s41
	s_cselect_b32 s75, s52, s40
	s_add_i32 s76, s45, -2
	s_add_u32 s50, s50, 0x80080
	s_addc_u32 s51, s51, 0
	s_add_u32 s77, s52, 0x100
	v_mov_b32_e32 v32, 0
	s_addc_u32 s78, s53, 0
	s_mov_b32 s52, 0
	v_mov_b32_e32 v33, v32
	v_mov_b32_e32 v34, v32
	v_mov_b32_e32 v35, v32
	v_mov_b32_e32 v36, v32
	v_mov_b32_e32 v37, v32
	v_mov_b32_e32 v38, v32
	v_mov_b32_e32 v39, v32
	v_mov_b32_e32 v40, v32
	v_mov_b32_e32 v41, v32
	v_mov_b32_e32 v42, v32
	v_mov_b32_e32 v43, v32
	v_mov_b32_e32 v48, v32
	v_mov_b32_e32 v49, v32
	v_mov_b32_e32 v50, v32
	v_mov_b32_e32 v51, v32
	v_mov_b32_e32 v60, v32
	v_mov_b32_e32 v61, v32
	v_mov_b32_e32 v62, v32
	v_mov_b32_e32 v63, v32
	v_mov_b32_e32 v64, v32
	v_mov_b32_e32 v65, v32
	v_mov_b32_e32 v66, v32
	v_mov_b32_e32 v67, v32
	v_mov_b32_e32 v76, v32
	v_mov_b32_e32 v77, v32
	v_mov_b32_e32 v78, v32
	v_mov_b32_e32 v79, v32
	v_mov_b32_e32 v80, v32
	v_mov_b32_e32 v81, v32
	v_mov_b32_e32 v82, v32
	v_mov_b32_e32 v83, v32
	v_mov_b32_e32 v44, v32
	v_mov_b32_e32 v45, v32
	v_mov_b32_e32 v46, v32
	v_mov_b32_e32 v47, v32
	v_mov_b32_e32 v52, v32
	v_mov_b32_e32 v53, v32
	v_mov_b32_e32 v54, v32
	v_mov_b32_e32 v55, v32
	v_mov_b32_e32 v56, v32
	v_mov_b32_e32 v57, v32
	v_mov_b32_e32 v58, v32
	v_mov_b32_e32 v59, v32
	v_mov_b32_e32 v68, v32
	v_mov_b32_e32 v69, v32
	v_mov_b32_e32 v70, v32
	v_mov_b32_e32 v71, v32
	v_mov_b32_e32 v72, v32
	v_mov_b32_e32 v73, v32
	v_mov_b32_e32 v74, v32
	v_mov_b32_e32 v75, v32
	v_mov_b32_e32 v84, v32
	v_mov_b32_e32 v85, v32
	v_mov_b32_e32 v86, v32
	v_mov_b32_e32 v87, v32
	v_mov_b32_e32 v88, v32
	v_mov_b32_e32 v89, v32
	v_mov_b32_e32 v90, v32
	v_mov_b32_e32 v91, v32
	v_mov_b32_e32 v92, v32
	v_mov_b32_e32 v93, v32
	v_mov_b32_e32 v94, v32
	v_mov_b32_e32 v95, v32
	v_mov_b32_e32 v96, v32
	v_mov_b32_e32 v97, v32
	v_mov_b32_e32 v98, v32
	v_mov_b32_e32 v99, v32
	v_mov_b32_e32 v100, v32
	v_mov_b32_e32 v101, v32
	v_mov_b32_e32 v102, v32
	v_mov_b32_e32 v103, v32
	v_mov_b32_e32 v104, v32
	v_mov_b32_e32 v105, v32
	v_mov_b32_e32 v106, v32
	v_mov_b32_e32 v107, v32
	v_mov_b32_e32 v112, v32
	v_mov_b32_e32 v113, v32
	v_mov_b32_e32 v114, v32
	v_mov_b32_e32 v115, v32
	v_mov_b32_e32 v120, v32
	v_mov_b32_e32 v121, v32
	v_mov_b32_e32 v122, v32
	v_mov_b32_e32 v123, v32
	v_mov_b32_e32 v128, v32
	v_mov_b32_e32 v129, v32
	v_mov_b32_e32 v130, v32
	v_mov_b32_e32 v131, v32
	v_mov_b32_e32 v136, v32
	v_mov_b32_e32 v137, v32
	v_mov_b32_e32 v138, v32
	v_mov_b32_e32 v139, v32
	v_mov_b32_e32 v144, v32
	v_mov_b32_e32 v145, v32
	v_mov_b32_e32 v146, v32
	v_mov_b32_e32 v147, v32
	v_mov_b32_e32 v108, v32
	v_mov_b32_e32 v109, v32
	v_mov_b32_e32 v110, v32
	v_mov_b32_e32 v111, v32
	v_mov_b32_e32 v116, v32
	v_mov_b32_e32 v117, v32
	v_mov_b32_e32 v118, v32
	v_mov_b32_e32 v119, v32
	v_mov_b32_e32 v124, v32
	v_mov_b32_e32 v125, v32
	v_mov_b32_e32 v126, v32
	v_mov_b32_e32 v127, v32
	v_mov_b32_e32 v132, v32
	v_mov_b32_e32 v133, v32
	v_mov_b32_e32 v134, v32
	v_mov_b32_e32 v135, v32
	v_mov_b32_e32 v140, v32
	v_mov_b32_e32 v141, v32
	v_mov_b32_e32 v142, v32
	v_mov_b32_e32 v143, v32
	v_mov_b32_e32 v148, v32
	v_mov_b32_e32 v149, v32
	v_mov_b32_e32 v150, v32
	v_mov_b32_e32 v151, v32
	v_mov_b32_e32 v152, v32
	v_mov_b32_e32 v153, v32
	v_mov_b32_e32 v154, v32
	v_mov_b32_e32 v155, v32
	v_mov_b32_e32 v156, v32
	v_mov_b32_e32 v157, v32
	v_mov_b32_e32 v158, v32
	v_mov_b32_e32 v159, v32
	v_readlane_b32 s98, v250, 9
	s_nop 1
	s_cmp_lt_u32 s98, 4
	s_cbranch_scc1 .Lprio_skip4
	s_setprio 1
.Lprio_skip4:
.LBB0_1588:
	ds_read_b128 v[24:27], v218
	ds_read_b128 v[28:31], v218 offset:1024
	ds_read_b128 v[16:19], v218 offset:2048
	ds_read_b128 v[20:23], v218 offset:3072
	ds_read_b128 v[8:11], v219
	ds_read_b128 v[12:15], v219 offset:1024
	ds_read_b128 v[0:3], v219 offset:2048
	ds_read_b128 v[4:7], v219 offset:3072
	s_add_i32 s79, s52, 2
	s_add_u32 s53, s50, 0xfff80080
	s_addc_u32 s54, s51, -1
	s_cmp_eq_u32 s76, s52
	s_cselect_b32 s52, s75, s77
	s_cselect_b32 s55, s31, s54
	s_cselect_b32 s54, s37, s53
	s_cselect_b32 s53, s35, s78
	s_add_i32 m0, s47, 0xc000
	ds_read_b128 v[160:163], v220
	ds_read_b128 v[164:167], v220 offset:1024
	ds_read_b128 v[168:171], v220 offset:2048
	ds_read_b128 v[172:175], v220 offset:3072
	ds_read_b128 v[176:179], v220 offset:4096
	ds_read_b128 v[180:183], v220 offset:5120
	ds_read_b128 v[184:187], v220 offset:6144
	ds_read_b128 v[188:191], v220 offset:7168
	global_load_lds_dwordx4 v196, s[50:51]
	s_add_i32 m0, s47, 0xe000
	s_nop 0
	global_load_lds_dwordx4 v198, s[50:51]
	s_waitcnt vmcnt(8)
	s_waitcnt lgkmcnt(0)
	s_barrier
	s_waitcnt lgkmcnt(0)
	v_mfma_f32_16x16x128_f8f6f4 v[156:159], v[24:31], v[160:167], v[156:159]
	v_mfma_f32_16x16x128_f8f6f4 v[152:155], v[16:23], v[160:167], v[152:155]
	v_mfma_f32_16x16x128_f8f6f4 v[148:151], v[24:31], v[168:175], v[148:151]
	v_mfma_f32_16x16x128_f8f6f4 v[140:143], v[16:23], v[168:175], v[140:143]
	v_mfma_f32_16x16x128_f8f6f4 v[132:135], v[24:31], v[176:183], v[132:135]
	v_mfma_f32_16x16x128_f8f6f4 v[124:127], v[16:23], v[176:183], v[124:127]
	v_mfma_f32_16x16x128_f8f6f4 v[116:119], v[24:31], v[184:191], v[116:119]
	v_mfma_f32_16x16x128_f8f6f4 v[108:111], v[16:23], v[184:191], v[108:111]
	v_mfma_f32_16x16x128_f8f6f4 v[144:147], v[8:15], v[160:167], v[144:147]
	v_mfma_f32_16x16x128_f8f6f4 v[136:139], v[0:7], v[160:167], v[136:139]
	v_mfma_f32_16x16x128_f8f6f4 v[128:131], v[8:15], v[168:175], v[128:131]
	v_mfma_f32_16x16x128_f8f6f4 v[120:123], v[0:7], v[168:175], v[120:123]
	v_mfma_f32_16x16x128_f8f6f4 v[112:115], v[8:15], v[176:183], v[112:115]
	v_mfma_f32_16x16x128_f8f6f4 v[104:107], v[0:7], v[176:183], v[104:107]
	v_mfma_f32_16x16x128_f8f6f4 v[100:103], v[8:15], v[184:191], v[100:103]
	v_mfma_f32_16x16x128_f8f6f4 v[96:99], v[0:7], v[184:191], v[96:99]
	s_barrier
	s_add_i32 s80, s66, s93
	s_mov_b32 m0, s80
	ds_read_b128 v[168:171], v220 offset:16384
	ds_read_b128 v[172:175], v220 offset:17408
	ds_read_b128 v[176:179], v220 offset:18432
	ds_read_b128 v[180:183], v220 offset:19456
	ds_read_b128 v[184:187], v220 offset:20480
	ds_read_b128 v[188:191], v220 offset:21504
	ds_read_b128 v[202:205], v220 offset:22528
	ds_read_b128 v[206:209], v220 offset:23552
	global_load_lds_dwordx4 v192, s[52:53]
	s_add_i32 m0, s80, 0x2000
	s_add_u32 s80, s52, 0x80000
	v_lshl_add_u64 v[162:163], s[52:53], 0, v[194:195]
	s_addc_u32 s81, s53, 0
	s_add_i32 s82, s68, s93
	global_load_lds_dwordx4 v194, s[52:53]
	s_mov_b32 m0, s82
	v_lshl_add_u64 v[166:167], s[54:55], 0, v[194:195]
	global_load_lds_dwordx4 v192, s[80:81]
	s_add_i32 m0, s82, 0x2000
	s_nop 0
	global_load_lds_dwordx4 v194, s[80:81]
	v_lshl_add_u64 v[164:165], s[54:55], 0, v[192:193]
	s_mov_b32 m0, s47
	s_nop 0
	global_load_lds_dwordx4 v192, s[54:55]
	s_mov_b32 m0, s58
	s_nop 0
	global_load_lds_dwordx4 v194, s[54:55]
	s_waitcnt vmcnt(8)
	s_waitcnt lgkmcnt(0)
	s_barrier
	s_waitcnt lgkmcnt(0)
	v_mfma_f32_16x16x128_f8f6f4 v[92:95], v[24:31], v[168:175], v[92:95]
	v_mfma_f32_16x16x128_f8f6f4 v[88:91], v[16:23], v[168:175], v[88:91]
	v_mfma_f32_16x16x128_f8f6f4 v[84:87], v[24:31], v[176:183], v[84:87]
	v_mfma_f32_16x16x128_f8f6f4 v[72:75], v[16:23], v[176:183], v[72:75]
	v_mfma_f32_16x16x128_f8f6f4 v[68:71], v[24:31], v[184:191], v[68:71]
	v_mfma_f32_16x16x128_f8f6f4 v[56:59], v[16:23], v[184:191], v[56:59]
	v_mfma_f32_16x16x128_f8f6f4 v[52:55], v[24:31], v[202:209], v[52:55]
	v_mfma_f32_16x16x128_f8f6f4 v[44:47], v[16:23], v[202:209], v[44:47]
	v_mfma_f32_16x16x128_f8f6f4 v[80:83], v[8:15], v[168:175], v[80:83]
	v_mfma_f32_16x16x128_f8f6f4 v[76:79], v[0:7], v[168:175], v[76:79]
	v_mfma_f32_16x16x128_f8f6f4 v[64:67], v[8:15], v[176:183], v[64:67]
	v_mfma_f32_16x16x128_f8f6f4 v[60:63], v[0:7], v[176:183], v[60:63]
	v_mfma_f32_16x16x128_f8f6f4 v[48:51], v[8:15], v[184:191], v[48:51]
	v_mfma_f32_16x16x128_f8f6f4 v[40:43], v[0:7], v[184:191], v[40:43]
	v_mfma_f32_16x16x128_f8f6f4 v[36:39], v[8:15], v[202:209], v[36:39]
	v_mfma_f32_16x16x128_f8f6f4 v[32:35], v[0:7], v[202:209], v[32:35]
	s_barrier
	s_add_i32 s80, 0, 0x18000
	s_add_i32 s81, 0, 0x1c000
	v_add_u32_e32 v12, s80, v215
	v_add_u32_e32 v28, s81, v215
	ds_read_b128 v[0:3], v12
	ds_read_b128 v[4:7], v12 offset:1024
	ds_read_b128 v[8:11], v12 offset:2048
	ds_read_b128 v[12:15], v12 offset:3072
	ds_read_b128 v[16:19], v28
	ds_read_b128 v[20:23], v28 offset:1024
	ds_read_b128 v[24:27], v28 offset:2048
	ds_read_b128 v[28:31], v28 offset:3072
	s_add_u32 s54, s54, 0x80000
	s_addc_u32 s55, s55, 0
	s_mov_b32 m0, s59
	ds_read_b128 v[168:171], v220 offset:32768
	ds_read_b128 v[172:175], v220 offset:33792
	ds_read_b128 v[176:179], v220 offset:34816
	ds_read_b128 v[180:183], v220 offset:35840
	ds_read_b128 v[184:187], v220 offset:36864
	ds_read_b128 v[188:191], v220 offset:37888
	ds_read_b128 v[202:205], v220 offset:38912
	ds_read_b128 v[206:209], v220 offset:39936
	global_load_lds_dwordx4 v192, s[54:55]
	s_mov_b32 m0, s60
	s_nop 0
	global_load_lds_dwordx4 v194, s[54:55]
	s_waitcnt vmcnt(8)
	s_waitcnt lgkmcnt(0)
	s_barrier
	s_waitcnt lgkmcnt(0)
	v_mfma_f32_16x16x128_f8f6f4 v[156:159], v[0:7], v[168:175], v[156:159]
	v_mfma_f32_16x16x128_f8f6f4 v[152:155], v[8:15], v[168:175], v[152:155]
	v_mfma_f32_16x16x128_f8f6f4 v[148:151], v[0:7], v[176:183], v[148:151]
	v_mfma_f32_16x16x128_f8f6f4 v[140:143], v[8:15], v[176:183], v[140:143]
	v_mfma_f32_16x16x128_f8f6f4 v[132:135], v[0:7], v[184:191], v[132:135]
	v_mfma_f32_16x16x128_f8f6f4 v[124:127], v[8:15], v[184:191], v[124:127]
	v_mfma_f32_16x16x128_f8f6f4 v[116:119], v[0:7], v[202:209], v[116:119]
	v_mfma_f32_16x16x128_f8f6f4 v[108:111], v[8:15], v[202:209], v[108:111]
	v_mfma_f32_16x16x128_f8f6f4 v[144:147], v[16:23], v[168:175], v[144:147]
	v_mfma_f32_16x16x128_f8f6f4 v[136:139], v[24:31], v[168:175], v[136:139]
	v_mfma_f32_16x16x128_f8f6f4 v[128:131], v[16:23], v[176:183], v[128:131]
	v_mfma_f32_16x16x128_f8f6f4 v[120:123], v[24:31], v[176:183], v[120:123]
	v_mfma_f32_16x16x128_f8f6f4 v[112:115], v[16:23], v[184:191], v[112:115]
	v_mfma_f32_16x16x128_f8f6f4 v[104:107], v[24:31], v[184:191], v[104:107]
	v_mfma_f32_16x16x128_f8f6f4 v[100:103], v[16:23], v[202:209], v[100:103]
	v_mfma_f32_16x16x128_f8f6f4 v[96:99], v[24:31], v[202:209], v[96:99]
	s_barrier
	s_add_i32 s54, s80, s93
	s_add_i32 m0, s54, 0xffffff80
	ds_read_b128 v[168:171], v220 offset:49152
	ds_read_b128 v[172:175], v220 offset:50176
	ds_read_b128 v[176:179], v220 offset:51200
	ds_read_b128 v[180:183], v220 offset:52224
	ds_read_b128 v[184:187], v220 offset:53248
	ds_read_b128 v[188:191], v220 offset:54272
	ds_read_b128 v[202:205], v220 offset:55296
	ds_read_b128 v[206:209], v220 offset:56320
	global_load_lds_dwordx4 v192, s[52:53] offset:128
	s_add_i32 m0, s54, 0x2000
	s_add_u32 s52, s52, 0x80080
	v_lshl_add_u64 v[160:161], v[162:163], 0, s[24:25]
	s_addc_u32 s53, s53, 0
	s_add_i32 s54, s81, s93
	global_load_lds_dwordx4 v[160:161], off
	s_mov_b32 m0, s54
	s_nop 0
	global_load_lds_dwordx4 v192, s[52:53]
	s_add_i32 m0, s54, 0x2000
	s_nop 0
	global_load_lds_dwordx4 v194, s[52:53]
	v_lshl_add_u64 v[160:161], v[164:165], 0, s[24:25]
	s_mov_b32 m0, s64
	s_nop 0
	global_load_lds_dwordx4 v[160:161], off
	v_lshl_add_u64 v[160:161], v[166:167], 0, s[24:25]
	s_mov_b32 m0, s65
	s_nop 0
	global_load_lds_dwordx4 v[160:161], off
	s_waitcnt vmcnt(8)
	s_waitcnt lgkmcnt(0)
	s_barrier
	s_waitcnt lgkmcnt(0)
	v_mfma_f32_16x16x128_f8f6f4 v[92:95], v[0:7], v[168:175], v[92:95]
	v_mfma_f32_16x16x128_f8f6f4 v[88:91], v[8:15], v[168:175], v[88:91]
	v_mfma_f32_16x16x128_f8f6f4 v[84:87], v[0:7], v[176:183], v[84:87]
	v_mfma_f32_16x16x128_f8f6f4 v[72:75], v[8:15], v[176:183], v[72:75]
	v_mfma_f32_16x16x128_f8f6f4 v[68:71], v[0:7], v[184:191], v[68:71]
	v_mfma_f32_16x16x128_f8f6f4 v[56:59], v[8:15], v[184:191], v[56:59]
	v_mfma_f32_16x16x128_f8f6f4 v[52:55], v[0:7], v[202:209], v[52:55]
	v_mfma_f32_16x16x128_f8f6f4 v[44:47], v[8:15], v[202:209], v[44:47]
	v_mfma_f32_16x16x128_f8f6f4 v[80:83], v[16:23], v[168:175], v[80:83]
	v_mfma_f32_16x16x128_f8f6f4 v[76:79], v[24:31], v[168:175], v[76:79]
	v_mfma_f32_16x16x128_f8f6f4 v[64:67], v[16:23], v[176:183], v[64:67]
	v_mfma_f32_16x16x128_f8f6f4 v[60:63], v[24:31], v[176:183], v[60:63]
	v_mfma_f32_16x16x128_f8f6f4 v[48:51], v[16:23], v[184:191], v[48:51]
	v_mfma_f32_16x16x128_f8f6f4 v[40:43], v[24:31], v[184:191], v[40:43]
	v_mfma_f32_16x16x128_f8f6f4 v[36:39], v[16:23], v[202:209], v[36:39]
	v_mfma_f32_16x16x128_f8f6f4 v[32:35], v[24:31], v[202:209], v[32:35]
	s_barrier
	s_add_u32 s50, s50, 0x100
	s_addc_u32 s51, s51, 0
	s_add_u32 s77, s77, 0x100
	s_addc_u32 s78, s78, 0
	s_cmp_ge_i32 s79, s45
	s_mov_b32 s52, s79
	s_cbranch_scc0 .LBB0_1588
	s_setprio 0
	s_nop 15
	s_nop 15
	s_andn2_b64 vcc, exec, s[48:49]
	s_cbranch_vccnz .LBB0_1602
	global_load_dword v0, v193, s[6:7] sc1
	s_waitcnt vmcnt(0)
	v_cmp_le_u32_e32 vcc, s88, v0
	s_cbranch_vccnz .LBB0_1601
	s_mov_b32 s31, 0x3ffff8
	s_branch .LBB0_1593
